# branch-merge phase: LDS ring continues across tiles, next tile's first two chunks prefetched under the last chunk
# baseline (speedup 1.0000x reference)
; #define LAS __attribute__((address_space(3)))
; __device__ __forceinline__ int ltid(int wv) { unsigned z = 0u; asm volatile("" : "+v"(z)); return wv * 64 + (int)__builtin_amdgcn_mbcnt_hi(~0u, __builtin_amdgcn_mbcnt_lo(~0u, z)); }
; __device__ __forceinline__ int lgrid() { int g = gridDim.x; asm volatile("" : "+s"(g)); return g; }
; __device__ __forceinline__ int lbid() { int b = blockIdx.x; asm volatile("" : "+s"(b)); return b; }
; __device__ __forceinline__ void branch_phase(LAS unsigned char* lds, const bf16_t* __restrict__ O, const bf16_t* __restrict__ Wb, const bf16_t* __restrict__ Gt, bf16_t* __restrict__ MG, int tg, int wv) {
;     const int tid = ltid(wv), lane = tid & 63, wave = tid >> 6, wm = wave >> 2, wn = wave & 3, fr = lane & 15, fq = lane >> 4;
;     const int G_ = lgrid(), b_ = lbid(), vb = (G_ % 8 == 0) ? (b_ % 8) * (G_ / 8) + b_ / 8 : b_;
;     const int ntile = (tg / 128) * 4;
;     constexpr int STG = 49152;
;     int pR[2], pC[2];
; #pragma unroll
;     for (int i = 0; i < 2; ++i) pg8::stage_rc(tid * 16 + i * 8192, pR[i], pC[i]);
;     const int aoff = pg8::lds_byte(wm * 64 + fr, fq * 8), boff = 16384 + (wn >> 1) * 16384 + pg8::lds_byte((wn & 1) * 64 + fr, fq * 8);
;     __syncthreads();
;     for (int tile = vb; tile < ntile; tile += G_) {
;         const int rt = tile >> 2, ct = tile & 3;
;         const bf16_t* Ab = O + (size_t)(rt * 128) * 1024;
;         u32x2 sum[4][4];
; #pragma unroll
;         for (int m = 0; m < 4; ++m)
; #pragma unroll
;             for (int n = 0; n < 4; ++n) sum[m][n] = (u32x2){0u, 0u};
;     ...
;         BR_LOAD(0, 0);
;         asm volatile("s_waitcnt vmcnt(0)" ::: "memory"); __syncthreads();
.LBB0_276:
	s_lshr_b32 s6, s51, 5
	s_cmp_ge_i32 s5, s6
	s_waitcnt vmcnt(0) lgkmcnt(0)
	s_barrier
	s_cbranch_scc1 .LBB0_283
	v_mbcnt_lo_u32_b32 v196, -1, 0
	v_mbcnt_hi_u32_b32 v196, -1, v196
	v_readlane_b32 s78, v255, 1
	s_nop 1
	s_lshr_b32 s9, s78, 6
	s_lshl_b32 s78, s78, 4
	v_lshlrev_b32_e32 v206, 4, v196
	v_and_b32_e32 v207, 32, v196
	v_xor_b32_e32 v206, v206, v207
	v_lshrrev_b32_e32 v207, 6, v206
	s_lshr_b32 s10, s9, 1
	s_lshl_b32 s10, s10, 4
	v_add_u32_e32 v207, s10, v207
	v_and_b32_e32 v208, 63, v206
	v_lshrrev_b32_e32 v208, 1, v208
	s_and_b32 s10, s9, 1
	s_lshl_b32 s10, s10, 5
	v_add_u32_e32 v208, s10, v208
	v_lshlrev_b32_e32 v208, 1, v208
	v_lshl_add_u32 v197, v207, 11, v208
	v_add_u32_e32 v198, 0x20000, v197
	v_lshl_add_u32 v199, v207, 9, v208
	v_add_u32_e32 v200, 0x8000, v199
	v_and_b32_e32 v206, 15, v196
	v_lshrrev_b32_e32 v207, 4, v196
	v_lshlrev_b32_e32 v208, 6, v206
	v_lshl_add_u32 v208, v207, 4, v208
	v_lshlrev_b32_e32 v209, 2, v206
	v_and_b32_e32 v209, 32, v209
	v_xor_b32_e32 v208, v208, v209
	s_lshr_b32 s10, s9, 2
	s_lshl_b32 s11, s10, 13
	v_add_u32_e32 v201, s11, v208
	s_and_b32 s11, s9, 3
	s_and_b32 s12, s11, 1
	s_lshl_b32 s12, s12, 13
	s_lshr_b32 s13, s11, 1
	s_lshl_b32 s21, s13, 14
	s_add_i32 s12, s12, s21
	s_add_i32 s12, s12, 0x4000
	v_add_u32_e32 v202, s12, v208
	s_lshl_b32 s21, s13, 11
	v_add_u32_e32 v203, s21, v202
	v_add_u32_e32 v214, 0x0, v201
	v_add_u32_e32 v217, 0x0, v202
	v_add_u32_e32 v215, 0xc000, v201
	v_add_u32_e32 v218, 0xc000, v202
	v_add_u32_e32 v216, 0x18000, v201
	v_add_u32_e32 v219, 0x18000, v203
	s_add_i32 s82, s78, 0x0
	s_add_i32 s85, s78, 0x8000
	s_add_i32 s83, s78, 0xc000
	s_add_i32 s60, s78, 0x14000
	s_add_i32 s84, s78, 0x18000
	s_add_i32 s61, s78, 0x20800
	s_lshl_b32 s12, s10, 6
	v_add_u32_e32 v210, s12, v206
	s_lshl_b32 s12, s11, 7
	v_lshl_add_u32 v211, v207, 3, s12
	v_lshl_add_u32 v204, v210, 13, v211
	v_and_b32_e32 v211, 1, v207
	v_lshlrev_b32_e32 v211, 5, v211
	v_lshrrev_b32_e32 v212, 1, v207
	v_lshl_add_u32 v211, v212, 4, v211
	v_add_u32_e32 v211, s12, v211
	v_lshl_add_u32 v205, v210, 11, v211
	s_lshr_b32 s9, s5, 2
	s_and_b32 s10, s5, 3
	s_lshl_b32 s11, s9, 18
	s_add_u32 s64, s18, s11
	s_addc_u32 s65, s19, 0
	s_add_u32 s64, s64, 0x1e200000
	s_addc_u32 s65, s65, 0
	s_lshl_b32 s11, s10, 17
	s_add_u32 s68, s57, s11
	s_addc_u32 s69, s58, 0
	s_add_u32 s68, s68, 0x1100000
	s_addc_u32 s69, s69, 0
	s_lshl_b32 s11, s9, 20
	s_lshl_b32 s12, s10, 9
	s_add_u32 s74, s18, s11
	s_addc_u32 s75, s19, 0
	s_add_u32 s74, s74, s12
	s_addc_u32 s75, s75, 0
	s_add_u32 s74, s74, 0xa200000
	s_addc_u32 s75, s75, 0
	s_lshl_b32 s11, s9, 18
	s_add_u32 s76, s18, s11
	s_addc_u32 s77, s19, 0
	s_add_u32 s76, s76, s12
	s_addc_u32 s77, s77, 0
	s_add_u32 s76, s76, 0x29400000
	s_addc_u32 s77, s77, 0
	s_lshr_b32 s62, s4, 2
	s_lshl_b32 s62, s62, 18
	s_waitcnt lgkmcnt(0)
	s_barrier
	s_add_u32 s66, s64, 0x0
	s_addc_u32 s67, s65, 0
	s_add_u32 s70, s68, 0x0
	s_addc_u32 s71, s69, 0
	s_add_u32 s72, s70, 0x10000
	s_addc_u32 s73, s71, 0
	s_mov_b32 m0, s82
	s_nop 0
	global_load_lds_dwordx4 v197, s[66:67]
	s_add_i32 m0, s82, 0x2000
	s_nop 0
	global_load_lds_dwordx4 v198, s[66:67]
	s_add_i32 m0, s82, 0x4000
	s_nop 0
	global_load_lds_dwordx4 v199, s[70:71]
	s_add_i32 m0, s82, 0x6000
	s_nop 0
	global_load_lds_dwordx4 v200, s[70:71]
	s_mov_b32 m0, s85
	s_nop 0
	global_load_lds_dwordx4 v199, s[72:73]
	s_add_i32 m0, s85, 0x2000
	s_nop 0
	global_load_lds_dwordx4 v200, s[72:73]
	s_add_u32 s66, s64, 0x80
	s_addc_u32 s67, s65, 0
	s_add_u32 s70, s68, 0x80
	s_addc_u32 s71, s69, 0
	s_add_u32 s72, s70, 0x10000
	s_addc_u32 s73, s71, 0
	s_mov_b32 m0, s83
	s_nop 0
	global_load_lds_dwordx4 v197, s[66:67]
	s_add_i32 m0, s83, 0x2000
	s_nop 0
	global_load_lds_dwordx4 v198, s[66:67]
	s_add_i32 m0, s83, 0x4000
	s_nop 0
	global_load_lds_dwordx4 v199, s[70:71]
	s_add_i32 m0, s83, 0x6000
	s_nop 0
	global_load_lds_dwordx4 v200, s[70:71]
	s_mov_b32 m0, s60
	s_nop 0
	global_load_lds_dwordx4 v199, s[72:73]
	s_add_i32 m0, s60, 0x2000
	s_nop 0
	global_load_lds_dwordx4 v200, s[72:73]
.Lph6_tile:
	v_mov_b64 v[66:67], 0
	v_mov_b64 v[68:69], 0
	v_mov_b64 v[70:71], 0
	v_mov_b64 v[72:73], 0
	v_mov_b64 v[74:75], 0
	v_mov_b64 v[76:77], 0
	v_mov_b64 v[78:79], 0
	v_mov_b64 v[80:81], 0
	v_mov_b64 v[82:83], 0
	v_mov_b64 v[84:85], 0
	v_mov_b64 v[86:87], 0
	v_mov_b64 v[88:89], 0
	v_mov_b64 v[90:91], 0
	v_mov_b64 v[92:93], 0
	v_mov_b64 v[94:95], 0
	v_mov_b64 v[96:97], 0
	s_waitcnt vmcnt(6)
	s_barrier
; #define LAS __attribute__((address_space(3)))
; __device__ __forceinline__ void branch_phase(LAS unsigned char* lds, const bf16_t* __restrict__ O, const bf16_t* __restrict__ Wb, const bf16_t* __restrict__ Gt, bf16_t* __restrict__ MG, int tg, int wv) {
;     ...
;         BR_LOAD(0, 0);
;         asm volatile("s_waitcnt vmcnt(0)" ::: "memory"); __syncthreads();
;         for (int j = 0; j < 4; ++j) {
;             u32x2 gv[4][4];
;             f32x4 acc[4][4];
; #pragma unroll
;             for (int m = 0; m < 4; ++m)
; #pragma unroll
;                 for (int n = 0; n < 4; ++n) acc[m][n] = (f32x4){0.f, 0.f, 0.f, 0.f};
;             for (int kc = 0; kc < 4; ++kc) {
;                 const int c = j * 4 + kc;
;                 if (c + 1 < 16) BR_LOAD(c + 1, (c + 1) & 1);
;                 if (kc == 3) {
;                     const bf16_t* gp = Gt + (size_t)(rt * 128 + wm * 64 + fr) * ZC + j * 1024 + ct * 256 + wn * 64 + 4 * fq;
; #pragma unroll
;                     for (int m = 0; m < 4; ++m)
; #pragma unroll
;                         for (int n = 0; n < 4; ++n) gv[m][n] = *(const u32x2*)(gp + (size_t)m * 16 * ZC + n * 16);
;                 }
;                 LAS const unsigned char* st = lds + (c & 1) * STG;
; #pragma unroll
;                 for (int k = 0; k < 2; ++k) {
;                     __builtin_amdgcn_sched_barrier(0);
;                     bf16x8 af[4], bfr[4];
; #pragma unroll
;                     for (int m = 0; m < 4; ++m) af[m] = *(LAS const bf16x8*)(st + aoff + m * 2048 + k * 1024);
; #pragma unroll
;                     for (int n = 0; n < 4; ++n) bfr[n] = *(LAS const bf16x8*)(st + boff + n * 2048 + k * 1024);
; #pragma unroll
;                     for (int m = 0; m < 4; ++m)
; #pragma unroll
;                         for (int n = 0; n < 4; ++n) acc[m][n] = __builtin_amdgcn_mfma_f32_16x16x32_bf16(bfr[n], af[m], acc[m][n], 0, 0, 0);
	s_add_u32 s66, s64, 0x100
	s_addc_u32 s67, s65, 0
	s_add_u32 s70, s68, 0x100
	s_addc_u32 s71, s69, 0
	s_add_u32 s72, s70, 0x10000
	s_addc_u32 s73, s71, 0
	s_mov_b32 m0, s84
	s_nop 0
	global_load_lds_dwordx4 v197, s[66:67]
	s_add_i32 m0, s84, 0x2000
	s_nop 0
	global_load_lds_dwordx4 v198, s[66:67]
	s_add_i32 m0, s84, 0x4000
	s_nop 0
	global_load_lds_dwordx4 v199, s[70:71]
	s_add_i32 m0, s84, 0x6000
	s_nop 0
	global_load_lds_dwordx4 v200, s[70:71]
	s_mov_b32 m0, s61
	s_nop 0
	global_load_lds_dwordx4 v199, s[72:73]
	s_add_i32 m0, s61, 0x2000
	s_nop 0
	global_load_lds_dwordx4 v200, s[72:73]
	ds_read_b128 v[130:133], v214 offset:0
	ds_read_b128 v[134:137], v214 offset:2048
	ds_read_b128 v[138:141], v214 offset:4096
	ds_read_b128 v[142:145], v214 offset:6144
	ds_read_b128 v[162:165], v217 offset:0
	ds_read_b128 v[166:169], v217 offset:2048
	ds_read_b128 v[170:173], v217 offset:4096
	ds_read_b128 v[174:177], v217 offset:6144
	ds_read_b128 v[146:149], v214 offset:1024
	ds_read_b128 v[150:153], v214 offset:3072
	ds_read_b128 v[154:157], v214 offset:5120
	ds_read_b128 v[158:161], v214 offset:7168
	ds_read_b128 v[178:181], v217 offset:1024
	ds_read_b128 v[182:185], v217 offset:3072
	ds_read_b128 v[186:189], v217 offset:5120
	ds_read_b128 v[190:193], v217 offset:7168
	s_waitcnt lgkmcnt(8)
	v_mfma_f32_16x16x32_bf16 v[2:5], v[162:165], v[130:133], 0
	v_mfma_f32_16x16x32_bf16 v[6:9], v[166:169], v[130:133], 0
	v_mfma_f32_16x16x32_bf16 v[10:13], v[170:173], v[130:133], 0
	v_mfma_f32_16x16x32_bf16 v[14:17], v[174:177], v[130:133], 0
	v_mfma_f32_16x16x32_bf16 v[18:21], v[162:165], v[134:137], 0
	v_mfma_f32_16x16x32_bf16 v[22:25], v[166:169], v[134:137], 0
	v_mfma_f32_16x16x32_bf16 v[26:29], v[170:173], v[134:137], 0
	v_mfma_f32_16x16x32_bf16 v[30:33], v[174:177], v[134:137], 0
	v_mfma_f32_16x16x32_bf16 v[34:37], v[162:165], v[138:141], 0
	v_mfma_f32_16x16x32_bf16 v[38:41], v[166:169], v[138:141], 0
	v_mfma_f32_16x16x32_bf16 v[42:45], v[170:173], v[138:141], 0
	v_mfma_f32_16x16x32_bf16 v[46:49], v[174:177], v[138:141], 0
	v_mfma_f32_16x16x32_bf16 v[50:53], v[162:165], v[142:145], 0
	v_mfma_f32_16x16x32_bf16 v[54:57], v[166:169], v[142:145], 0
	v_mfma_f32_16x16x32_bf16 v[58:61], v[170:173], v[142:145], 0
	v_mfma_f32_16x16x32_bf16 v[62:65], v[174:177], v[142:145], 0
	s_waitcnt lgkmcnt(0)
	v_mfma_f32_16x16x32_bf16 v[2:5], v[178:181], v[146:149], v[2:5]
	v_mfma_f32_16x16x32_bf16 v[6:9], v[182:185], v[146:149], v[6:9]
	v_mfma_f32_16x16x32_bf16 v[10:13], v[186:189], v[146:149], v[10:13]
	v_mfma_f32_16x16x32_bf16 v[14:17], v[190:193], v[146:149], v[14:17]
	v_mfma_f32_16x16x32_bf16 v[18:21], v[178:181], v[150:153], v[18:21]
	v_mfma_f32_16x16x32_bf16 v[22:25], v[182:185], v[150:153], v[22:25]
	v_mfma_f32_16x16x32_bf16 v[26:29], v[186:189], v[150:153], v[26:29]
	v_mfma_f32_16x16x32_bf16 v[30:33], v[190:193], v[150:153], v[30:33]
	v_mfma_f32_16x16x32_bf16 v[34:37], v[178:181], v[154:157], v[34:37]
	v_mfma_f32_16x16x32_bf16 v[38:41], v[182:185], v[154:157], v[38:41]
	v_mfma_f32_16x16x32_bf16 v[42:45], v[186:189], v[154:157], v[42:45]
	v_mfma_f32_16x16x32_bf16 v[46:49], v[190:193], v[154:157], v[46:49]
	v_mfma_f32_16x16x32_bf16 v[50:53], v[178:181], v[158:161], v[50:53]
	v_mfma_f32_16x16x32_bf16 v[54:57], v[182:185], v[158:161], v[54:57]
	v_mfma_f32_16x16x32_bf16 v[58:61], v[186:189], v[158:161], v[58:61]
	v_mfma_f32_16x16x32_bf16 v[62:65], v[190:193], v[158:161], v[62:65]
	s_waitcnt vmcnt(6)
	s_barrier
	s_add_u32 s66, s64, 0x180
	s_addc_u32 s67, s65, 0
	s_add_u32 s70, s68, 0x180
	s_addc_u32 s71, s69, 0
	s_add_u32 s72, s70, 0x10000
	s_addc_u32 s73, s71, 0
	s_mov_b32 m0, s82
	s_nop 0
	global_load_lds_dwordx4 v197, s[66:67]
	s_add_i32 m0, s82, 0x2000
	s_nop 0
	global_load_lds_dwordx4 v198, s[66:67]
	s_add_i32 m0, s82, 0x4000
	s_nop 0
	global_load_lds_dwordx4 v199, s[70:71]
	s_add_i32 m0, s82, 0x6000
	s_nop 0
	global_load_lds_dwordx4 v200, s[70:71]
	s_mov_b32 m0, s85
	s_nop 0
	global_load_lds_dwordx4 v199, s[72:73]
	s_add_i32 m0, s85, 0x2000
	s_nop 0
	global_load_lds_dwordx4 v200, s[72:73]
	s_add_u32 s80, s74, 0x0
	s_addc_u32 s81, s75, 0
	global_load_dwordx2 v[98:99], v204, s[80:81] offset:0
	global_load_dwordx2 v[100:101], v204, s[80:81] offset:32
	global_load_dwordx2 v[102:103], v204, s[80:81] offset:64
	global_load_dwordx2 v[104:105], v204, s[80:81] offset:96
	s_add_u32 s80, s80, 0x20000
	s_addc_u32 s81, s81, 0
	global_load_dwordx2 v[106:107], v204, s[80:81] offset:0
	global_load_dwordx2 v[108:109], v204, s[80:81] offset:32
	global_load_dwordx2 v[110:111], v204, s[80:81] offset:64
	global_load_dwordx2 v[112:113], v204, s[80:81] offset:96
	s_add_u32 s80, s80, 0x20000
	s_addc_u32 s81, s81, 0
	global_load_dwordx2 v[114:115], v204, s[80:81] offset:0
	global_load_dwordx2 v[116:117], v204, s[80:81] offset:32
	global_load_dwordx2 v[118:119], v204, s[80:81] offset:64
	global_load_dwordx2 v[120:121], v204, s[80:81] offset:96
	s_add_u32 s80, s80, 0x20000
	s_addc_u32 s81, s81, 0
	global_load_dwordx2 v[122:123], v204, s[80:81] offset:0
	global_load_dwordx2 v[124:125], v204, s[80:81] offset:32
	global_load_dwordx2 v[126:127], v204, s[80:81] offset:64
	global_load_dwordx2 v[128:129], v204, s[80:81] offset:96
	ds_read_b128 v[130:133], v215 offset:0
	ds_read_b128 v[134:137], v215 offset:2048
	ds_read_b128 v[138:141], v215 offset:4096
	ds_read_b128 v[142:145], v215 offset:6144
	ds_read_b128 v[162:165], v218 offset:0
	ds_read_b128 v[166:169], v218 offset:2048
	ds_read_b128 v[170:173], v218 offset:4096
	ds_read_b128 v[174:177], v218 offset:6144
	ds_read_b128 v[146:149], v215 offset:1024
	ds_read_b128 v[150:153], v215 offset:3072
	ds_read_b128 v[154:157], v215 offset:5120
	ds_read_b128 v[158:161], v215 offset:7168
	ds_read_b128 v[178:181], v218 offset:1024
	ds_read_b128 v[182:185], v218 offset:3072
	ds_read_b128 v[186:189], v218 offset:5120
	ds_read_b128 v[190:193], v218 offset:7168
	s_waitcnt lgkmcnt(8)
; #define LAS __attribute__((address_space(3)))
; __device__ __forceinline__ void branch_phase(LAS unsigned char* lds, const bf16_t* __restrict__ O, const bf16_t* __restrict__ Wb, const bf16_t* __restrict__ Gt, bf16_t* __restrict__ MG, int tg, int wv) {
;     ...
;         BR_LOAD(0, 0);
;         asm volatile("s_waitcnt vmcnt(0)" ::: "memory"); __syncthreads();
;         for (int j = 0; j < 4; ++j) {
;             u32x2 gv[4][4];
;             f32x4 acc[4][4];
; #pragma unroll
;             for (int m = 0; m < 4; ++m)
; #pragma unroll
;                 for (int n = 0; n < 4; ++n) acc[m][n] = (f32x4){0.f, 0.f, 0.f, 0.f};
;             for (int kc = 0; kc < 4; ++kc) {
;                 const int c = j * 4 + kc;
;                 if (c + 1 < 16) BR_LOAD(c + 1, (c + 1) & 1);
;                 if (kc == 3) {
;                     const bf16_t* gp = Gt + (size_t)(rt * 128 + wm * 64 + fr) * ZC + j * 1024 + ct * 256 + wn * 64 + 4 * fq;
; #pragma unroll
;                     for (int m = 0; m < 4; ++m)
; #pragma unroll
;                         for (int n = 0; n < 4; ++n) gv[m][n] = *(const u32x2*)(gp + (size_t)m * 16 * ZC + n * 16);
;                 }
;                 LAS const unsigned char* st = lds + (c & 1) * STG;
; #pragma unroll
;                 for (int k = 0; k < 2; ++k) {
;                     __builtin_amdgcn_sched_barrier(0);
;                     bf16x8 af[4], bfr[4];
; #pragma unroll
;                     for (int m = 0; m < 4; ++m) af[m] = *(LAS const bf16x8*)(st + aoff + m * 2048 + k * 1024);
; #pragma unroll
;                     for (int n = 0; n < 4; ++n) bfr[n] = *(LAS const bf16x8*)(st + boff + n * 2048 + k * 1024);
; #pragma unroll
;                     for (int m = 0; m < 4; ++m)
; #pragma unroll
;                         for (int n = 0; n < 4; ++n) acc[m][n] = __builtin_amdgcn_mfma_f32_16x16x32_bf16(bfr[n], af[m], acc[m][n], 0, 0, 0);
;                 }
;                 asm volatile("s_waitcnt vmcnt(0)" ::: "memory"); __syncthreads();
	v_mfma_f32_16x16x32_bf16 v[2:5], v[162:165], v[130:133], v[2:5]
	v_mfma_f32_16x16x32_bf16 v[6:9], v[166:169], v[130:133], v[6:9]
	v_mfma_f32_16x16x32_bf16 v[10:13], v[170:173], v[130:133], v[10:13]
	v_mfma_f32_16x16x32_bf16 v[14:17], v[174:177], v[130:133], v[14:17]
	v_mfma_f32_16x16x32_bf16 v[18:21], v[162:165], v[134:137], v[18:21]
	v_mfma_f32_16x16x32_bf16 v[22:25], v[166:169], v[134:137], v[22:25]
	v_mfma_f32_16x16x32_bf16 v[26:29], v[170:173], v[134:137], v[26:29]
	v_mfma_f32_16x16x32_bf16 v[30:33], v[174:177], v[134:137], v[30:33]
	v_mfma_f32_16x16x32_bf16 v[34:37], v[162:165], v[138:141], v[34:37]
	v_mfma_f32_16x16x32_bf16 v[38:41], v[166:169], v[138:141], v[38:41]
	v_mfma_f32_16x16x32_bf16 v[42:45], v[170:173], v[138:141], v[42:45]
	v_mfma_f32_16x16x32_bf16 v[46:49], v[174:177], v[138:141], v[46:49]
	v_mfma_f32_16x16x32_bf16 v[50:53], v[162:165], v[142:145], v[50:53]
	v_mfma_f32_16x16x32_bf16 v[54:57], v[166:169], v[142:145], v[54:57]
	v_mfma_f32_16x16x32_bf16 v[58:61], v[170:173], v[142:145], v[58:61]
	v_mfma_f32_16x16x32_bf16 v[62:65], v[174:177], v[142:145], v[62:65]
	s_waitcnt lgkmcnt(0)
	v_mfma_f32_16x16x32_bf16 v[2:5], v[178:181], v[146:149], v[2:5]
	v_mfma_f32_16x16x32_bf16 v[6:9], v[182:185], v[146:149], v[6:9]
	v_mfma_f32_16x16x32_bf16 v[10:13], v[186:189], v[146:149], v[10:13]
	v_mfma_f32_16x16x32_bf16 v[14:17], v[190:193], v[146:149], v[14:17]
	v_mfma_f32_16x16x32_bf16 v[18:21], v[178:181], v[150:153], v[18:21]
	v_mfma_f32_16x16x32_bf16 v[22:25], v[182:185], v[150:153], v[22:25]
	v_mfma_f32_16x16x32_bf16 v[26:29], v[186:189], v[150:153], v[26:29]
	v_mfma_f32_16x16x32_bf16 v[30:33], v[190:193], v[150:153], v[30:33]
	v_mfma_f32_16x16x32_bf16 v[34:37], v[178:181], v[154:157], v[34:37]
	v_mfma_f32_16x16x32_bf16 v[38:41], v[182:185], v[154:157], v[38:41]
	v_mfma_f32_16x16x32_bf16 v[42:45], v[186:189], v[154:157], v[42:45]
	v_mfma_f32_16x16x32_bf16 v[46:49], v[190:193], v[154:157], v[46:49]
	v_mfma_f32_16x16x32_bf16 v[50:53], v[178:181], v[158:161], v[50:53]
	v_mfma_f32_16x16x32_bf16 v[54:57], v[182:185], v[158:161], v[54:57]
	v_mfma_f32_16x16x32_bf16 v[58:61], v[186:189], v[158:161], v[58:61]
	v_mfma_f32_16x16x32_bf16 v[62:65], v[190:193], v[158:161], v[62:65]
	s_waitcnt vmcnt(22)
	s_barrier
	s_add_u32 s66, s64, 0x200
	s_addc_u32 s67, s65, 0
	s_add_u32 s70, s68, 0x80000
	s_addc_u32 s71, s69, 0
	s_add_u32 s72, s70, 0x10000
	s_addc_u32 s73, s71, 0
	s_mov_b32 m0, s83
	s_nop 0
	global_load_lds_dwordx4 v197, s[66:67]
	s_add_i32 m0, s83, 0x2000
	s_nop 0
	global_load_lds_dwordx4 v198, s[66:67]
	s_add_i32 m0, s83, 0x4000
	s_nop 0
	global_load_lds_dwordx4 v199, s[70:71]
	s_add_i32 m0, s83, 0x6000
	s_nop 0
	global_load_lds_dwordx4 v200, s[70:71]
	s_mov_b32 m0, s60
	s_nop 0
	global_load_lds_dwordx4 v199, s[72:73]
	s_add_i32 m0, s60, 0x2000
	s_nop 0
	global_load_lds_dwordx4 v200, s[72:73]
	ds_read_b128 v[130:133], v216 offset:0
	ds_read_b128 v[134:137], v216 offset:2048
	ds_read_b128 v[138:141], v216 offset:4096
	ds_read_b128 v[142:145], v216 offset:6144
	ds_read_b128 v[162:165], v219 offset:0
	ds_read_b128 v[166:169], v219 offset:2048
	ds_read_b128 v[170:173], v219 offset:4096
	ds_read_b128 v[174:177], v219 offset:6144
	ds_read_b128 v[146:149], v216 offset:1024
	ds_read_b128 v[150:153], v216 offset:3072
	ds_read_b128 v[154:157], v216 offset:5120
	ds_read_b128 v[158:161], v216 offset:7168
	ds_read_b128 v[178:181], v219 offset:1024
	ds_read_b128 v[182:185], v219 offset:3072
	ds_read_b128 v[186:189], v219 offset:5120
	ds_read_b128 v[190:193], v219 offset:7168
	s_waitcnt lgkmcnt(8)
	v_mfma_f32_16x16x32_bf16 v[2:5], v[162:165], v[130:133], v[2:5]
	v_mfma_f32_16x16x32_bf16 v[6:9], v[166:169], v[130:133], v[6:9]
	v_mfma_f32_16x16x32_bf16 v[10:13], v[170:173], v[130:133], v[10:13]
	v_mfma_f32_16x16x32_bf16 v[14:17], v[174:177], v[130:133], v[14:17]
	v_mfma_f32_16x16x32_bf16 v[18:21], v[162:165], v[134:137], v[18:21]
	v_mfma_f32_16x16x32_bf16 v[22:25], v[166:169], v[134:137], v[22:25]
	v_mfma_f32_16x16x32_bf16 v[26:29], v[170:173], v[134:137], v[26:29]
	v_mfma_f32_16x16x32_bf16 v[30:33], v[174:177], v[134:137], v[30:33]
	v_mfma_f32_16x16x32_bf16 v[34:37], v[162:165], v[138:141], v[34:37]
	v_mfma_f32_16x16x32_bf16 v[38:41], v[166:169], v[138:141], v[38:41]
	v_mfma_f32_16x16x32_bf16 v[42:45], v[170:173], v[138:141], v[42:45]
	v_mfma_f32_16x16x32_bf16 v[46:49], v[174:177], v[138:141], v[46:49]
	v_mfma_f32_16x16x32_bf16 v[50:53], v[162:165], v[142:145], v[50:53]
	v_mfma_f32_16x16x32_bf16 v[54:57], v[166:169], v[142:145], v[54:57]
	v_mfma_f32_16x16x32_bf16 v[58:61], v[170:173], v[142:145], v[58:61]
	v_mfma_f32_16x16x32_bf16 v[62:65], v[174:177], v[142:145], v[62:65]
	s_waitcnt lgkmcnt(0)
	v_mfma_f32_16x16x32_bf16 v[2:5], v[178:181], v[146:149], v[2:5]
	v_mfma_f32_16x16x32_bf16 v[6:9], v[182:185], v[146:149], v[6:9]
	v_mfma_f32_16x16x32_bf16 v[10:13], v[186:189], v[146:149], v[10:13]
	v_mfma_f32_16x16x32_bf16 v[14:17], v[190:193], v[146:149], v[14:17]
	v_mfma_f32_16x16x32_bf16 v[18:21], v[178:181], v[150:153], v[18:21]
	v_mfma_f32_16x16x32_bf16 v[22:25], v[182:185], v[150:153], v[22:25]
	v_mfma_f32_16x16x32_bf16 v[26:29], v[186:189], v[150:153], v[26:29]
	v_mfma_f32_16x16x32_bf16 v[30:33], v[190:193], v[150:153], v[30:33]
	v_mfma_f32_16x16x32_bf16 v[34:37], v[178:181], v[154:157], v[34:37]
	v_mfma_f32_16x16x32_bf16 v[38:41], v[182:185], v[154:157], v[38:41]
	v_mfma_f32_16x16x32_bf16 v[42:45], v[186:189], v[154:157], v[42:45]
	v_mfma_f32_16x16x32_bf16 v[46:49], v[190:193], v[154:157], v[46:49]
	v_mfma_f32_16x16x32_bf16 v[50:53], v[178:181], v[158:161], v[50:53]
	v_mfma_f32_16x16x32_bf16 v[54:57], v[182:185], v[158:161], v[54:57]
	v_mfma_f32_16x16x32_bf16 v[58:61], v[186:189], v[158:161], v[58:61]
	v_mfma_f32_16x16x32_bf16 v[62:65], v[190:193], v[158:161], v[62:65]
	s_waitcnt vmcnt(22)
	s_barrier
; #define LAS __attribute__((address_space(3)))
; __device__ __forceinline__ void branch_phase(LAS unsigned char* lds, const bf16_t* __restrict__ O, const bf16_t* __restrict__ Wb, const bf16_t* __restrict__ Gt, bf16_t* __restrict__ MG, int tg, int wv) {
;     ...
;             for (int kc = 0; kc < 4; ++kc) {
;                 const int c = j * 4 + kc;
;                 if (c + 1 < 16) BR_LOAD(c + 1, (c + 1) & 1);
;                 if (kc == 3) {
;                     const bf16_t* gp = Gt + (size_t)(rt * 128 + wm * 64 + fr) * ZC + j * 1024 + ct * 256 + wn * 64 + 4 * fq;
; #pragma unroll
;                     for (int m = 0; m < 4; ++m)
; #pragma unroll
;                         for (int n = 0; n < 4; ++n) gv[m][n] = *(const u32x2*)(gp + (size_t)m * 16 * ZC + n * 16);
;                 }
;                 LAS const unsigned char* st = lds + (c & 1) * STG;
; #pragma unroll
;                 for (int k = 0; k < 2; ++k) {
;                     __builtin_amdgcn_sched_barrier(0);
;                     bf16x8 af[4], bfr[4];
; #pragma unroll
;                     for (int m = 0; m < 4; ++m) af[m] = *(LAS const bf16x8*)(st + aoff + m * 2048 + k * 1024);
; #pragma unroll
;                     for (int n = 0; n < 4; ++n) bfr[n] = *(LAS const bf16x8*)(st + boff + n * 2048 + k * 1024);
; #pragma unroll
;                     for (int m = 0; m < 4; ++m)
; #pragma unroll
;                         for (int n = 0; n < 4; ++n) acc[m][n] = __builtin_amdgcn_mfma_f32_16x16x32_bf16(bfr[n], af[m], acc[m][n], 0, 0, 0);
;                 }
;                 asm volatile("s_waitcnt vmcnt(0)" ::: "memory"); __syncthreads();
;             }
; #pragma unroll
;             for (int m = 0; m < 4; ++m)
; #pragma unroll
;                 for (int n = 0; n < 4; ++n) { const u32x2 g = gv[m][n], sp = sum[m][n];
;                     const float s0_ = __builtin_bit_cast(float, sp.x << 16) + acc[m][n][0] * __builtin_bit_cast(float, g.x << 16), s1_ = __builtin_bit_cast(float, sp.x & 0xffff0000u) + acc[m][n][1] * __builtin_bit_cast(float, g.x & 0xffff0000u);
;                     const float s2_ = __builtin_bit_cast(float, sp.y << 16) + acc[m][n][2] * __builtin_bit_cast(float, g.y << 16), s3_ = __builtin_bit_cast(float, sp.y & 0xffff0000u) + acc[m][n][3] * __builtin_bit_cast(float, g.y & 0xffff0000u);
;                     sum[m][n] = (u32x2){cvtpk(s0_, s1_), cvtpk(s2_, s3_)}; }
	s_add_u32 s66, s64, 0x280
	s_addc_u32 s67, s65, 0
	s_add_u32 s70, s68, 0x80080
	s_addc_u32 s71, s69, 0
	s_add_u32 s72, s70, 0x10000
	s_addc_u32 s73, s71, 0
	s_mov_b32 m0, s84
	s_nop 0
	global_load_lds_dwordx4 v197, s[66:67]
	s_add_i32 m0, s84, 0x2000
	s_nop 0
	global_load_lds_dwordx4 v198, s[66:67]
	s_add_i32 m0, s84, 0x4000
	s_nop 0
	global_load_lds_dwordx4 v199, s[70:71]
	s_add_i32 m0, s84, 0x6000
	s_nop 0
	global_load_lds_dwordx4 v200, s[70:71]
	s_mov_b32 m0, s61
	s_nop 0
	global_load_lds_dwordx4 v199, s[72:73]
	s_add_i32 m0, s61, 0x2000
	s_nop 0
	global_load_lds_dwordx4 v200, s[72:73]
	ds_read_b128 v[130:133], v214 offset:0
	ds_read_b128 v[134:137], v214 offset:2048
	ds_read_b128 v[138:141], v214 offset:4096
	ds_read_b128 v[142:145], v214 offset:6144
	ds_read_b128 v[162:165], v217 offset:0
	ds_read_b128 v[166:169], v217 offset:2048
	ds_read_b128 v[170:173], v217 offset:4096
	ds_read_b128 v[174:177], v217 offset:6144
	ds_read_b128 v[146:149], v214 offset:1024
	ds_read_b128 v[150:153], v214 offset:3072
	ds_read_b128 v[154:157], v214 offset:5120
	ds_read_b128 v[158:161], v214 offset:7168
	ds_read_b128 v[178:181], v217 offset:1024
	ds_read_b128 v[182:185], v217 offset:3072
	ds_read_b128 v[186:189], v217 offset:5120
	ds_read_b128 v[190:193], v217 offset:7168
	s_waitcnt lgkmcnt(8)
	v_mfma_f32_16x16x32_bf16 v[2:5], v[162:165], v[130:133], v[2:5]
	v_mfma_f32_16x16x32_bf16 v[6:9], v[166:169], v[130:133], v[6:9]
	v_mfma_f32_16x16x32_bf16 v[10:13], v[170:173], v[130:133], v[10:13]
	v_mfma_f32_16x16x32_bf16 v[14:17], v[174:177], v[130:133], v[14:17]
	v_mfma_f32_16x16x32_bf16 v[18:21], v[162:165], v[134:137], v[18:21]
	v_mfma_f32_16x16x32_bf16 v[22:25], v[166:169], v[134:137], v[22:25]
	v_mfma_f32_16x16x32_bf16 v[26:29], v[170:173], v[134:137], v[26:29]
	v_mfma_f32_16x16x32_bf16 v[30:33], v[174:177], v[134:137], v[30:33]
	v_mfma_f32_16x16x32_bf16 v[34:37], v[162:165], v[138:141], v[34:37]
	v_mfma_f32_16x16x32_bf16 v[38:41], v[166:169], v[138:141], v[38:41]
	v_mfma_f32_16x16x32_bf16 v[42:45], v[170:173], v[138:141], v[42:45]
	v_mfma_f32_16x16x32_bf16 v[46:49], v[174:177], v[138:141], v[46:49]
	v_mfma_f32_16x16x32_bf16 v[50:53], v[162:165], v[142:145], v[50:53]
	v_mfma_f32_16x16x32_bf16 v[54:57], v[166:169], v[142:145], v[54:57]
	v_mfma_f32_16x16x32_bf16 v[58:61], v[170:173], v[142:145], v[58:61]
	v_mfma_f32_16x16x32_bf16 v[62:65], v[174:177], v[142:145], v[62:65]
	s_waitcnt lgkmcnt(0)
	v_mfma_f32_16x16x32_bf16 v[2:5], v[178:181], v[146:149], v[2:5]
	v_mfma_f32_16x16x32_bf16 v[6:9], v[182:185], v[146:149], v[6:9]
	v_mfma_f32_16x16x32_bf16 v[10:13], v[186:189], v[146:149], v[10:13]
	v_mfma_f32_16x16x32_bf16 v[14:17], v[190:193], v[146:149], v[14:17]
	v_mfma_f32_16x16x32_bf16 v[18:21], v[178:181], v[150:153], v[18:21]
	v_mfma_f32_16x16x32_bf16 v[22:25], v[182:185], v[150:153], v[22:25]
	v_mfma_f32_16x16x32_bf16 v[26:29], v[186:189], v[150:153], v[26:29]
	v_mfma_f32_16x16x32_bf16 v[30:33], v[190:193], v[150:153], v[30:33]
	v_mfma_f32_16x16x32_bf16 v[34:37], v[178:181], v[154:157], v[34:37]
	v_mfma_f32_16x16x32_bf16 v[38:41], v[182:185], v[154:157], v[38:41]
	v_mfma_f32_16x16x32_bf16 v[42:45], v[186:189], v[154:157], v[42:45]
	v_mfma_f32_16x16x32_bf16 v[46:49], v[190:193], v[154:157], v[46:49]
	v_mfma_f32_16x16x32_bf16 v[50:53], v[178:181], v[158:161], v[50:53]
	v_mfma_f32_16x16x32_bf16 v[54:57], v[182:185], v[158:161], v[54:57]
	v_mfma_f32_16x16x32_bf16 v[58:61], v[186:189], v[158:161], v[58:61]
	v_mfma_f32_16x16x32_bf16 v[62:65], v[190:193], v[158:161], v[62:65]
	s_waitcnt vmcnt(6)
	s_barrier
	s_nop 7
	v_lshlrev_b32_e32 v206, 16, v98
	v_and_b32_e32 v207, 0xffff0000, v98
	v_lshlrev_b32_e32 v208, 16, v99
	v_and_b32_e32 v209, 0xffff0000, v99
	v_lshlrev_b32_e32 v210, 16, v66
	v_and_b32_e32 v211, 0xffff0000, v66
	v_lshlrev_b32_e32 v212, 16, v67
	v_and_b32_e32 v213, 0xffff0000, v67
	v_pk_fma_f32 v[210:211], v[2:3], v[206:207], v[210:211]
	v_pk_fma_f32 v[212:213], v[4:5], v[208:209], v[212:213]
	v_cvt_pk_bf16_f32 v66, v210, v211
	v_cvt_pk_bf16_f32 v67, v212, v213
	v_lshlrev_b32_e32 v206, 16, v100
	v_and_b32_e32 v207, 0xffff0000, v100
	v_lshlrev_b32_e32 v208, 16, v101
	v_and_b32_e32 v209, 0xffff0000, v101
	v_lshlrev_b32_e32 v210, 16, v68
	v_and_b32_e32 v211, 0xffff0000, v68
	v_lshlrev_b32_e32 v212, 16, v69
	v_and_b32_e32 v213, 0xffff0000, v69
	v_pk_fma_f32 v[210:211], v[6:7], v[206:207], v[210:211]
	v_pk_fma_f32 v[212:213], v[8:9], v[208:209], v[212:213]
	v_cvt_pk_bf16_f32 v68, v210, v211
	v_cvt_pk_bf16_f32 v69, v212, v213
	v_lshlrev_b32_e32 v206, 16, v102
	v_and_b32_e32 v207, 0xffff0000, v102
	v_lshlrev_b32_e32 v208, 16, v103
	v_and_b32_e32 v209, 0xffff0000, v103
	v_lshlrev_b32_e32 v210, 16, v70
	v_and_b32_e32 v211, 0xffff0000, v70
	v_lshlrev_b32_e32 v212, 16, v71
	v_and_b32_e32 v213, 0xffff0000, v71
	v_pk_fma_f32 v[210:211], v[10:11], v[206:207], v[210:211]
	v_pk_fma_f32 v[212:213], v[12:13], v[208:209], v[212:213]
	v_cvt_pk_bf16_f32 v70, v210, v211
	v_cvt_pk_bf16_f32 v71, v212, v213
	v_lshlrev_b32_e32 v206, 16, v104
	v_and_b32_e32 v207, 0xffff0000, v104
	v_lshlrev_b32_e32 v208, 16, v105
	v_and_b32_e32 v209, 0xffff0000, v105
	v_lshlrev_b32_e32 v210, 16, v72
	v_and_b32_e32 v211, 0xffff0000, v72
	v_lshlrev_b32_e32 v212, 16, v73
	v_and_b32_e32 v213, 0xffff0000, v73
	v_pk_fma_f32 v[210:211], v[14:15], v[206:207], v[210:211]
	v_pk_fma_f32 v[212:213], v[16:17], v[208:209], v[212:213]
	v_cvt_pk_bf16_f32 v72, v210, v211
	v_cvt_pk_bf16_f32 v73, v212, v213
	v_lshlrev_b32_e32 v206, 16, v106
	v_and_b32_e32 v207, 0xffff0000, v106
	v_lshlrev_b32_e32 v208, 16, v107
	v_and_b32_e32 v209, 0xffff0000, v107
	v_lshlrev_b32_e32 v210, 16, v74
	v_and_b32_e32 v211, 0xffff0000, v74
; __device__ __forceinline__ void branch_phase(LAS unsigned char* lds, const bf16_t* __restrict__ O, const bf16_t* __restrict__ Wb, const bf16_t* __restrict__ Gt, bf16_t* __restrict__ MG, int tg, int wv) {
;     ...
;         BR_LOAD(0, 0);
;         asm volatile("s_waitcnt vmcnt(0)" ::: "memory"); __syncthreads();
;         for (int j = 0; j < 4; ++j) {
;             u32x2 gv[4][4];
;             f32x4 acc[4][4];
; #pragma unroll
;             for (int m = 0; m < 4; ++m)
; #pragma unroll
;                 for (int n = 0; n < 4; ++n) acc[m][n] = (f32x4){0.f, 0.f, 0.f, 0.f};
;             for (int kc = 0; kc < 4; ++kc) {
;                 const int c = j * 4 + kc;
;                 if (c + 1 < 16) BR_LOAD(c + 1, (c + 1) & 1);
;                 if (kc == 3) {
;                     const bf16_t* gp = Gt + (size_t)(rt * 128 + wm * 64 + fr) * ZC + j * 1024 + ct * 256 + wn * 64 + 4 * fq;
; #pragma unroll
;                     for (int m = 0; m < 4; ++m)
; #pragma unroll
;                         for (int n = 0; n < 4; ++n) gv[m][n] = *(const u32x2*)(gp + (size_t)m * 16 * ZC + n * 16);
;                 }
;                 LAS const unsigned char* st = lds + (c & 1) * STG;
; #pragma unroll
;                 for (int k = 0; k < 2; ++k) {
;                     __builtin_amdgcn_sched_barrier(0);
;                     bf16x8 af[4], bfr[4];
; #pragma unroll
;                     for (int m = 0; m < 4; ++m) af[m] = *(LAS const bf16x8*)(st + aoff + m * 2048 + k * 1024);
; #pragma unroll
;                     for (int n = 0; n < 4; ++n) bfr[n] = *(LAS const bf16x8*)(st + boff + n * 2048 + k * 1024);
; #pragma unroll
;     ...
; #pragma unroll
;             for (int m = 0; m < 4; ++m)
; #pragma unroll
;                 for (int n = 0; n < 4; ++n) { const u32x2 g = gv[m][n], sp = sum[m][n];
;                     const float s0_ = __builtin_bit_cast(float, sp.x << 16) + acc[m][n][0] * __builtin_bit_cast(float, g.x << 16), s1_ = __builtin_bit_cast(float, sp.x & 0xffff0000u) + acc[m][n][1] * __builtin_bit_cast(float, g.x & 0xffff0000u);
;                     const float s2_ = __builtin_bit_cast(float, sp.y << 16) + acc[m][n][2] * __builtin_bit_cast(float, g.y << 16), s3_ = __builtin_bit_cast(float, sp.y & 0xffff0000u) + acc[m][n][3] * __builtin_bit_cast(float, g.y & 0xffff0000u);
;                     sum[m][n] = (u32x2){cvtpk(s0_, s1_), cvtpk(s2_, s3_)}; }
	v_lshlrev_b32_e32 v212, 16, v75
	v_and_b32_e32 v213, 0xffff0000, v75
	v_pk_fma_f32 v[210:211], v[18:19], v[206:207], v[210:211]
	v_pk_fma_f32 v[212:213], v[20:21], v[208:209], v[212:213]
	v_cvt_pk_bf16_f32 v74, v210, v211
	v_cvt_pk_bf16_f32 v75, v212, v213
	v_lshlrev_b32_e32 v206, 16, v108
	v_and_b32_e32 v207, 0xffff0000, v108
	v_lshlrev_b32_e32 v208, 16, v109
	v_and_b32_e32 v209, 0xffff0000, v109
	v_lshlrev_b32_e32 v210, 16, v76
	v_and_b32_e32 v211, 0xffff0000, v76
	v_lshlrev_b32_e32 v212, 16, v77
	v_and_b32_e32 v213, 0xffff0000, v77
	v_pk_fma_f32 v[210:211], v[22:23], v[206:207], v[210:211]
	v_pk_fma_f32 v[212:213], v[24:25], v[208:209], v[212:213]
	v_cvt_pk_bf16_f32 v76, v210, v211
	v_cvt_pk_bf16_f32 v77, v212, v213
	v_lshlrev_b32_e32 v206, 16, v110
	v_and_b32_e32 v207, 0xffff0000, v110
	v_lshlrev_b32_e32 v208, 16, v111
	v_and_b32_e32 v209, 0xffff0000, v111
	v_lshlrev_b32_e32 v210, 16, v78
	v_and_b32_e32 v211, 0xffff0000, v78
	v_lshlrev_b32_e32 v212, 16, v79
	v_and_b32_e32 v213, 0xffff0000, v79
	v_pk_fma_f32 v[210:211], v[26:27], v[206:207], v[210:211]
	v_pk_fma_f32 v[212:213], v[28:29], v[208:209], v[212:213]
	v_cvt_pk_bf16_f32 v78, v210, v211
	v_cvt_pk_bf16_f32 v79, v212, v213
	v_lshlrev_b32_e32 v206, 16, v112
	v_and_b32_e32 v207, 0xffff0000, v112
	v_lshlrev_b32_e32 v208, 16, v113
	v_and_b32_e32 v209, 0xffff0000, v113
	v_lshlrev_b32_e32 v210, 16, v80
	v_and_b32_e32 v211, 0xffff0000, v80
	v_lshlrev_b32_e32 v212, 16, v81
	v_and_b32_e32 v213, 0xffff0000, v81
	v_pk_fma_f32 v[210:211], v[30:31], v[206:207], v[210:211]
	v_pk_fma_f32 v[212:213], v[32:33], v[208:209], v[212:213]
	v_cvt_pk_bf16_f32 v80, v210, v211
	v_cvt_pk_bf16_f32 v81, v212, v213
	v_lshlrev_b32_e32 v206, 16, v114
	v_and_b32_e32 v207, 0xffff0000, v114
	v_lshlrev_b32_e32 v208, 16, v115
	v_and_b32_e32 v209, 0xffff0000, v115
	v_lshlrev_b32_e32 v210, 16, v82
	v_and_b32_e32 v211, 0xffff0000, v82
	v_lshlrev_b32_e32 v212, 16, v83
	v_and_b32_e32 v213, 0xffff0000, v83
	v_pk_fma_f32 v[210:211], v[34:35], v[206:207], v[210:211]
	v_pk_fma_f32 v[212:213], v[36:37], v[208:209], v[212:213]
	v_cvt_pk_bf16_f32 v82, v210, v211
	v_cvt_pk_bf16_f32 v83, v212, v213
	v_lshlrev_b32_e32 v206, 16, v116
	v_and_b32_e32 v207, 0xffff0000, v116
	v_lshlrev_b32_e32 v208, 16, v117
	v_and_b32_e32 v209, 0xffff0000, v117
	v_lshlrev_b32_e32 v210, 16, v84
	v_and_b32_e32 v211, 0xffff0000, v84
	v_lshlrev_b32_e32 v212, 16, v85
	v_and_b32_e32 v213, 0xffff0000, v85
	v_pk_fma_f32 v[210:211], v[38:39], v[206:207], v[210:211]
	v_pk_fma_f32 v[212:213], v[40:41], v[208:209], v[212:213]
	v_cvt_pk_bf16_f32 v84, v210, v211
	v_cvt_pk_bf16_f32 v85, v212, v213
	v_lshlrev_b32_e32 v206, 16, v118
	v_and_b32_e32 v207, 0xffff0000, v118
	v_lshlrev_b32_e32 v208, 16, v119
	v_and_b32_e32 v209, 0xffff0000, v119
	v_lshlrev_b32_e32 v210, 16, v86
	v_and_b32_e32 v211, 0xffff0000, v86
	v_lshlrev_b32_e32 v212, 16, v87
	v_and_b32_e32 v213, 0xffff0000, v87
	v_pk_fma_f32 v[210:211], v[42:43], v[206:207], v[210:211]
	v_pk_fma_f32 v[212:213], v[44:45], v[208:209], v[212:213]
	v_cvt_pk_bf16_f32 v86, v210, v211
	v_cvt_pk_bf16_f32 v87, v212, v213
	v_lshlrev_b32_e32 v206, 16, v120
	v_and_b32_e32 v207, 0xffff0000, v120
	v_lshlrev_b32_e32 v208, 16, v121
	v_and_b32_e32 v209, 0xffff0000, v121
	v_lshlrev_b32_e32 v210, 16, v88
	v_and_b32_e32 v211, 0xffff0000, v88
	v_lshlrev_b32_e32 v212, 16, v89
	v_and_b32_e32 v213, 0xffff0000, v89
	v_pk_fma_f32 v[210:211], v[46:47], v[206:207], v[210:211]
	v_pk_fma_f32 v[212:213], v[48:49], v[208:209], v[212:213]
	v_cvt_pk_bf16_f32 v88, v210, v211
	v_cvt_pk_bf16_f32 v89, v212, v213
	v_lshlrev_b32_e32 v206, 16, v122
	v_and_b32_e32 v207, 0xffff0000, v122
	v_lshlrev_b32_e32 v208, 16, v123
	v_and_b32_e32 v209, 0xffff0000, v123
	v_lshlrev_b32_e32 v210, 16, v90
	v_and_b32_e32 v211, 0xffff0000, v90
	v_lshlrev_b32_e32 v212, 16, v91
	v_and_b32_e32 v213, 0xffff0000, v91
	v_pk_fma_f32 v[210:211], v[50:51], v[206:207], v[210:211]
	v_pk_fma_f32 v[212:213], v[52:53], v[208:209], v[212:213]
	v_cvt_pk_bf16_f32 v90, v210, v211
	v_cvt_pk_bf16_f32 v91, v212, v213
	v_lshlrev_b32_e32 v206, 16, v124
	v_and_b32_e32 v207, 0xffff0000, v124
	v_lshlrev_b32_e32 v208, 16, v125
	v_and_b32_e32 v209, 0xffff0000, v125
	v_lshlrev_b32_e32 v210, 16, v92
	v_and_b32_e32 v211, 0xffff0000, v92
	v_lshlrev_b32_e32 v212, 16, v93
	v_and_b32_e32 v213, 0xffff0000, v93
	v_pk_fma_f32 v[210:211], v[54:55], v[206:207], v[210:211]
	v_pk_fma_f32 v[212:213], v[56:57], v[208:209], v[212:213]
	v_cvt_pk_bf16_f32 v92, v210, v211
	v_cvt_pk_bf16_f32 v93, v212, v213
	v_lshlrev_b32_e32 v206, 16, v126
	v_and_b32_e32 v207, 0xffff0000, v126
	v_lshlrev_b32_e32 v208, 16, v127
	v_and_b32_e32 v209, 0xffff0000, v127
	v_lshlrev_b32_e32 v210, 16, v94
	v_and_b32_e32 v211, 0xffff0000, v94
	v_lshlrev_b32_e32 v212, 16, v95
	v_and_b32_e32 v213, 0xffff0000, v95
	v_pk_fma_f32 v[210:211], v[58:59], v[206:207], v[210:211]
	v_pk_fma_f32 v[212:213], v[60:61], v[208:209], v[212:213]
	v_cvt_pk_bf16_f32 v94, v210, v211
	v_cvt_pk_bf16_f32 v95, v212, v213
	v_lshlrev_b32_e32 v206, 16, v128
	v_and_b32_e32 v207, 0xffff0000, v128
	v_lshlrev_b32_e32 v208, 16, v129
	v_and_b32_e32 v209, 0xffff0000, v129
	v_lshlrev_b32_e32 v210, 16, v96
	v_and_b32_e32 v211, 0xffff0000, v96
	v_lshlrev_b32_e32 v212, 16, v97
	v_and_b32_e32 v213, 0xffff0000, v97
	v_pk_fma_f32 v[210:211], v[62:63], v[206:207], v[210:211]
	v_pk_fma_f32 v[212:213], v[64:65], v[208:209], v[212:213]
	v_cvt_pk_bf16_f32 v96, v210, v211
	v_cvt_pk_bf16_f32 v97, v212, v213
	s_add_u32 s66, s64, 0x300
	s_addc_u32 s67, s65, 0
	s_add_u32 s70, s68, 0x80100
	s_addc_u32 s71, s69, 0
	s_add_u32 s72, s70, 0x10000
	s_addc_u32 s73, s71, 0
	s_mov_b32 m0, s82
	s_nop 0
	global_load_lds_dwordx4 v197, s[66:67]
	s_add_i32 m0, s82, 0x2000
	s_nop 0
	global_load_lds_dwordx4 v198, s[66:67]
	s_add_i32 m0, s82, 0x4000
	s_nop 0
	global_load_lds_dwordx4 v199, s[70:71]
	s_add_i32 m0, s82, 0x6000
	s_nop 0
	global_load_lds_dwordx4 v200, s[70:71]
	s_mov_b32 m0, s85
	s_nop 0
	global_load_lds_dwordx4 v199, s[72:73]
	s_add_i32 m0, s85, 0x2000
	s_nop 0
	global_load_lds_dwordx4 v200, s[72:73]
	ds_read_b128 v[130:133], v215 offset:0
	ds_read_b128 v[134:137], v215 offset:2048
	ds_read_b128 v[138:141], v215 offset:4096
	ds_read_b128 v[142:145], v215 offset:6144
	ds_read_b128 v[162:165], v218 offset:0
	ds_read_b128 v[166:169], v218 offset:2048
	ds_read_b128 v[170:173], v218 offset:4096
	ds_read_b128 v[174:177], v218 offset:6144
	ds_read_b128 v[146:149], v215 offset:1024
	ds_read_b128 v[150:153], v215 offset:3072
	ds_read_b128 v[154:157], v215 offset:5120
	ds_read_b128 v[158:161], v215 offset:7168
	ds_read_b128 v[178:181], v218 offset:1024
	ds_read_b128 v[182:185], v218 offset:3072
	ds_read_b128 v[186:189], v218 offset:5120
	ds_read_b128 v[190:193], v218 offset:7168
	s_waitcnt lgkmcnt(8)
; #define LAS __attribute__((address_space(3)))
; __device__ __forceinline__ void branch_phase(LAS unsigned char* lds, const bf16_t* __restrict__ O, const bf16_t* __restrict__ Wb, const bf16_t* __restrict__ Gt, bf16_t* __restrict__ MG, int tg, int wv) {
;     ...
;         BR_LOAD(0, 0);
;         asm volatile("s_waitcnt vmcnt(0)" ::: "memory"); __syncthreads();
;         for (int j = 0; j < 4; ++j) {
;             u32x2 gv[4][4];
;             f32x4 acc[4][4];
; #pragma unroll
;             for (int m = 0; m < 4; ++m)
; #pragma unroll
;                 for (int n = 0; n < 4; ++n) acc[m][n] = (f32x4){0.f, 0.f, 0.f, 0.f};
;             for (int kc = 0; kc < 4; ++kc) {
;                 const int c = j * 4 + kc;
;                 if (c + 1 < 16) BR_LOAD(c + 1, (c + 1) & 1);
;                 if (kc == 3) {
;                     const bf16_t* gp = Gt + (size_t)(rt * 128 + wm * 64 + fr) * ZC + j * 1024 + ct * 256 + wn * 64 + 4 * fq;
; #pragma unroll
;                     for (int m = 0; m < 4; ++m)
; #pragma unroll
;                         for (int n = 0; n < 4; ++n) gv[m][n] = *(const u32x2*)(gp + (size_t)m * 16 * ZC + n * 16);
;                 }
;                 LAS const unsigned char* st = lds + (c & 1) * STG;
; #pragma unroll
;                 for (int k = 0; k < 2; ++k) {
;                     __builtin_amdgcn_sched_barrier(0);
;                     bf16x8 af[4], bfr[4];
; #pragma unroll
;                     for (int m = 0; m < 4; ++m) af[m] = *(LAS const bf16x8*)(st + aoff + m * 2048 + k * 1024);
; #pragma unroll
;                     for (int n = 0; n < 4; ++n) bfr[n] = *(LAS const bf16x8*)(st + boff + n * 2048 + k * 1024);
; #pragma unroll
;                     for (int m = 0; m < 4; ++m)
; #pragma unroll
;                         for (int n = 0; n < 4; ++n) acc[m][n] = __builtin_amdgcn_mfma_f32_16x16x32_bf16(bfr[n], af[m], acc[m][n], 0, 0, 0);
;                 }
;                 asm volatile("s_waitcnt vmcnt(0)" ::: "memory"); __syncthreads();
	v_mfma_f32_16x16x32_bf16 v[2:5], v[162:165], v[130:133], 0
	v_mfma_f32_16x16x32_bf16 v[6:9], v[166:169], v[130:133], 0
	v_mfma_f32_16x16x32_bf16 v[10:13], v[170:173], v[130:133], 0
	v_mfma_f32_16x16x32_bf16 v[14:17], v[174:177], v[130:133], 0
	v_mfma_f32_16x16x32_bf16 v[18:21], v[162:165], v[134:137], 0
	v_mfma_f32_16x16x32_bf16 v[22:25], v[166:169], v[134:137], 0
	v_mfma_f32_16x16x32_bf16 v[26:29], v[170:173], v[134:137], 0
	v_mfma_f32_16x16x32_bf16 v[30:33], v[174:177], v[134:137], 0
	v_mfma_f32_16x16x32_bf16 v[34:37], v[162:165], v[138:141], 0
	v_mfma_f32_16x16x32_bf16 v[38:41], v[166:169], v[138:141], 0
	v_mfma_f32_16x16x32_bf16 v[42:45], v[170:173], v[138:141], 0
	v_mfma_f32_16x16x32_bf16 v[46:49], v[174:177], v[138:141], 0
	v_mfma_f32_16x16x32_bf16 v[50:53], v[162:165], v[142:145], 0
	v_mfma_f32_16x16x32_bf16 v[54:57], v[166:169], v[142:145], 0
	v_mfma_f32_16x16x32_bf16 v[58:61], v[170:173], v[142:145], 0
	v_mfma_f32_16x16x32_bf16 v[62:65], v[174:177], v[142:145], 0
	s_waitcnt lgkmcnt(0)
	v_mfma_f32_16x16x32_bf16 v[2:5], v[178:181], v[146:149], v[2:5]
	v_mfma_f32_16x16x32_bf16 v[6:9], v[182:185], v[146:149], v[6:9]
	v_mfma_f32_16x16x32_bf16 v[10:13], v[186:189], v[146:149], v[10:13]
	v_mfma_f32_16x16x32_bf16 v[14:17], v[190:193], v[146:149], v[14:17]
	v_mfma_f32_16x16x32_bf16 v[18:21], v[178:181], v[150:153], v[18:21]
	v_mfma_f32_16x16x32_bf16 v[22:25], v[182:185], v[150:153], v[22:25]
	v_mfma_f32_16x16x32_bf16 v[26:29], v[186:189], v[150:153], v[26:29]
	v_mfma_f32_16x16x32_bf16 v[30:33], v[190:193], v[150:153], v[30:33]
	v_mfma_f32_16x16x32_bf16 v[34:37], v[178:181], v[154:157], v[34:37]
	v_mfma_f32_16x16x32_bf16 v[38:41], v[182:185], v[154:157], v[38:41]
	v_mfma_f32_16x16x32_bf16 v[42:45], v[186:189], v[154:157], v[42:45]
	v_mfma_f32_16x16x32_bf16 v[46:49], v[190:193], v[154:157], v[46:49]
	v_mfma_f32_16x16x32_bf16 v[50:53], v[178:181], v[158:161], v[50:53]
	v_mfma_f32_16x16x32_bf16 v[54:57], v[182:185], v[158:161], v[54:57]
	v_mfma_f32_16x16x32_bf16 v[58:61], v[186:189], v[158:161], v[58:61]
	v_mfma_f32_16x16x32_bf16 v[62:65], v[190:193], v[158:161], v[62:65]
	s_waitcnt vmcnt(6)
	s_barrier
	s_add_u32 s66, s64, 0x380
	s_addc_u32 s67, s65, 0
	s_add_u32 s70, s68, 0x80180
	s_addc_u32 s71, s69, 0
	s_add_u32 s72, s70, 0x10000
	s_addc_u32 s73, s71, 0
	s_mov_b32 m0, s83
	s_nop 0
	global_load_lds_dwordx4 v197, s[66:67]
	s_add_i32 m0, s83, 0x2000
	s_nop 0
	global_load_lds_dwordx4 v198, s[66:67]
	s_add_i32 m0, s83, 0x4000
	s_nop 0
	global_load_lds_dwordx4 v199, s[70:71]
	s_add_i32 m0, s83, 0x6000
	s_nop 0
	global_load_lds_dwordx4 v200, s[70:71]
	s_mov_b32 m0, s60
	s_nop 0
	global_load_lds_dwordx4 v199, s[72:73]
	s_add_i32 m0, s60, 0x2000
	s_nop 0
	global_load_lds_dwordx4 v200, s[72:73]
	s_add_u32 s80, s74, 0x800
	s_addc_u32 s81, s75, 0
	global_load_dwordx2 v[98:99], v204, s[80:81] offset:0
	global_load_dwordx2 v[100:101], v204, s[80:81] offset:32
	global_load_dwordx2 v[102:103], v204, s[80:81] offset:64
	global_load_dwordx2 v[104:105], v204, s[80:81] offset:96
	s_add_u32 s80, s80, 0x20000
	s_addc_u32 s81, s81, 0
	global_load_dwordx2 v[106:107], v204, s[80:81] offset:0
	global_load_dwordx2 v[108:109], v204, s[80:81] offset:32
	global_load_dwordx2 v[110:111], v204, s[80:81] offset:64
	global_load_dwordx2 v[112:113], v204, s[80:81] offset:96
	s_add_u32 s80, s80, 0x20000
	s_addc_u32 s81, s81, 0
	global_load_dwordx2 v[114:115], v204, s[80:81] offset:0
	global_load_dwordx2 v[116:117], v204, s[80:81] offset:32
	global_load_dwordx2 v[118:119], v204, s[80:81] offset:64
	global_load_dwordx2 v[120:121], v204, s[80:81] offset:96
	s_add_u32 s80, s80, 0x20000
	s_addc_u32 s81, s81, 0
	global_load_dwordx2 v[122:123], v204, s[80:81] offset:0
	global_load_dwordx2 v[124:125], v204, s[80:81] offset:32
	global_load_dwordx2 v[126:127], v204, s[80:81] offset:64
	global_load_dwordx2 v[128:129], v204, s[80:81] offset:96
	ds_read_b128 v[130:133], v216 offset:0
	ds_read_b128 v[134:137], v216 offset:2048
	ds_read_b128 v[138:141], v216 offset:4096
	ds_read_b128 v[142:145], v216 offset:6144
	ds_read_b128 v[162:165], v219 offset:0
	ds_read_b128 v[166:169], v219 offset:2048
	ds_read_b128 v[170:173], v219 offset:4096
	ds_read_b128 v[174:177], v219 offset:6144
	ds_read_b128 v[146:149], v216 offset:1024
	ds_read_b128 v[150:153], v216 offset:3072
	ds_read_b128 v[154:157], v216 offset:5120
	ds_read_b128 v[158:161], v216 offset:7168
	ds_read_b128 v[178:181], v219 offset:1024
	ds_read_b128 v[182:185], v219 offset:3072
	ds_read_b128 v[186:189], v219 offset:5120
	ds_read_b128 v[190:193], v219 offset:7168
	s_waitcnt lgkmcnt(8)
	v_mfma_f32_16x16x32_bf16 v[2:5], v[162:165], v[130:133], v[2:5]
	v_mfma_f32_16x16x32_bf16 v[6:9], v[166:169], v[130:133], v[6:9]
	v_mfma_f32_16x16x32_bf16 v[10:13], v[170:173], v[130:133], v[10:13]
	v_mfma_f32_16x16x32_bf16 v[14:17], v[174:177], v[130:133], v[14:17]
	v_mfma_f32_16x16x32_bf16 v[18:21], v[162:165], v[134:137], v[18:21]
	v_mfma_f32_16x16x32_bf16 v[22:25], v[166:169], v[134:137], v[22:25]
	v_mfma_f32_16x16x32_bf16 v[26:29], v[170:173], v[134:137], v[26:29]
	v_mfma_f32_16x16x32_bf16 v[30:33], v[174:177], v[134:137], v[30:33]
	v_mfma_f32_16x16x32_bf16 v[34:37], v[162:165], v[138:141], v[34:37]
	v_mfma_f32_16x16x32_bf16 v[38:41], v[166:169], v[138:141], v[38:41]
	v_mfma_f32_16x16x32_bf16 v[42:45], v[170:173], v[138:141], v[42:45]
	v_mfma_f32_16x16x32_bf16 v[46:49], v[174:177], v[138:141], v[46:49]
	v_mfma_f32_16x16x32_bf16 v[50:53], v[162:165], v[142:145], v[50:53]
	v_mfma_f32_16x16x32_bf16 v[54:57], v[166:169], v[142:145], v[54:57]
	v_mfma_f32_16x16x32_bf16 v[58:61], v[170:173], v[142:145], v[58:61]
	v_mfma_f32_16x16x32_bf16 v[62:65], v[174:177], v[142:145], v[62:65]
	s_waitcnt lgkmcnt(0)
	v_mfma_f32_16x16x32_bf16 v[2:5], v[178:181], v[146:149], v[2:5]
	v_mfma_f32_16x16x32_bf16 v[6:9], v[182:185], v[146:149], v[6:9]
	v_mfma_f32_16x16x32_bf16 v[10:13], v[186:189], v[146:149], v[10:13]
	v_mfma_f32_16x16x32_bf16 v[14:17], v[190:193], v[146:149], v[14:17]
	v_mfma_f32_16x16x32_bf16 v[18:21], v[178:181], v[150:153], v[18:21]
	v_mfma_f32_16x16x32_bf16 v[22:25], v[182:185], v[150:153], v[22:25]
	v_mfma_f32_16x16x32_bf16 v[26:29], v[186:189], v[150:153], v[26:29]
	v_mfma_f32_16x16x32_bf16 v[30:33], v[190:193], v[150:153], v[30:33]
	v_mfma_f32_16x16x32_bf16 v[34:37], v[178:181], v[154:157], v[34:37]
	v_mfma_f32_16x16x32_bf16 v[38:41], v[182:185], v[154:157], v[38:41]
	v_mfma_f32_16x16x32_bf16 v[42:45], v[186:189], v[154:157], v[42:45]
	v_mfma_f32_16x16x32_bf16 v[46:49], v[190:193], v[154:157], v[46:49]
	v_mfma_f32_16x16x32_bf16 v[50:53], v[178:181], v[158:161], v[50:53]
	v_mfma_f32_16x16x32_bf16 v[54:57], v[182:185], v[158:161], v[54:57]
	v_mfma_f32_16x16x32_bf16 v[58:61], v[186:189], v[158:161], v[58:61]
	v_mfma_f32_16x16x32_bf16 v[62:65], v[190:193], v[158:161], v[62:65]
	s_waitcnt vmcnt(22)
	s_barrier
; #define LAS __attribute__((address_space(3)))
; __device__ __forceinline__ void branch_phase(LAS unsigned char* lds, const bf16_t* __restrict__ O, const bf16_t* __restrict__ Wb, const bf16_t* __restrict__ Gt, bf16_t* __restrict__ MG, int tg, int wv) {
;     ...
;         BR_LOAD(0, 0);
;         asm volatile("s_waitcnt vmcnt(0)" ::: "memory"); __syncthreads();
;         for (int j = 0; j < 4; ++j) {
;             u32x2 gv[4][4];
;             f32x4 acc[4][4];
; #pragma unroll
;             for (int m = 0; m < 4; ++m)
; #pragma unroll
;                 for (int n = 0; n < 4; ++n) acc[m][n] = (f32x4){0.f, 0.f, 0.f, 0.f};
;             for (int kc = 0; kc < 4; ++kc) {
;                 const int c = j * 4 + kc;
;                 if (c + 1 < 16) BR_LOAD(c + 1, (c + 1) & 1);
;                 if (kc == 3) {
;                     const bf16_t* gp = Gt + (size_t)(rt * 128 + wm * 64 + fr) * ZC + j * 1024 + ct * 256 + wn * 64 + 4 * fq;
; #pragma unroll
;                     for (int m = 0; m < 4; ++m)
; #pragma unroll
;                         for (int n = 0; n < 4; ++n) gv[m][n] = *(const u32x2*)(gp + (size_t)m * 16 * ZC + n * 16);
;                 }
;                 LAS const unsigned char* st = lds + (c & 1) * STG;
; #pragma unroll
;                 for (int k = 0; k < 2; ++k) {
;                     __builtin_amdgcn_sched_barrier(0);
;                     bf16x8 af[4], bfr[4];
; #pragma unroll
;                     for (int m = 0; m < 4; ++m) af[m] = *(LAS const bf16x8*)(st + aoff + m * 2048 + k * 1024);
; #pragma unroll
;                     for (int n = 0; n < 4; ++n) bfr[n] = *(LAS const bf16x8*)(st + boff + n * 2048 + k * 1024);
; #pragma unroll
;                     for (int m = 0; m < 4; ++m)
; #pragma unroll
;                         for (int n = 0; n < 4; ++n) acc[m][n] = __builtin_amdgcn_mfma_f32_16x16x32_bf16(bfr[n], af[m], acc[m][n], 0, 0, 0);
	s_add_u32 s66, s64, 0x400
	s_addc_u32 s67, s65, 0
	s_add_u32 s70, s68, 0x100000
	s_addc_u32 s71, s69, 0
	s_add_u32 s72, s70, 0x10000
	s_addc_u32 s73, s71, 0
	s_mov_b32 m0, s84
	s_nop 0
	global_load_lds_dwordx4 v197, s[66:67]
	s_add_i32 m0, s84, 0x2000
	s_nop 0
	global_load_lds_dwordx4 v198, s[66:67]
	s_add_i32 m0, s84, 0x4000
	s_nop 0
	global_load_lds_dwordx4 v199, s[70:71]
	s_add_i32 m0, s84, 0x6000
	s_nop 0
	global_load_lds_dwordx4 v200, s[70:71]
	s_mov_b32 m0, s61
	s_nop 0
	global_load_lds_dwordx4 v199, s[72:73]
	s_add_i32 m0, s61, 0x2000
	s_nop 0
	global_load_lds_dwordx4 v200, s[72:73]
	ds_read_b128 v[130:133], v214 offset:0
	ds_read_b128 v[134:137], v214 offset:2048
	ds_read_b128 v[138:141], v214 offset:4096
	ds_read_b128 v[142:145], v214 offset:6144
	ds_read_b128 v[162:165], v217 offset:0
	ds_read_b128 v[166:169], v217 offset:2048
	ds_read_b128 v[170:173], v217 offset:4096
	ds_read_b128 v[174:177], v217 offset:6144
	ds_read_b128 v[146:149], v214 offset:1024
	ds_read_b128 v[150:153], v214 offset:3072
	ds_read_b128 v[154:157], v214 offset:5120
	ds_read_b128 v[158:161], v214 offset:7168
	ds_read_b128 v[178:181], v217 offset:1024
	ds_read_b128 v[182:185], v217 offset:3072
	ds_read_b128 v[186:189], v217 offset:5120
	ds_read_b128 v[190:193], v217 offset:7168
	s_waitcnt lgkmcnt(8)
	v_mfma_f32_16x16x32_bf16 v[2:5], v[162:165], v[130:133], v[2:5]
	v_mfma_f32_16x16x32_bf16 v[6:9], v[166:169], v[130:133], v[6:9]
	v_mfma_f32_16x16x32_bf16 v[10:13], v[170:173], v[130:133], v[10:13]
	v_mfma_f32_16x16x32_bf16 v[14:17], v[174:177], v[130:133], v[14:17]
	v_mfma_f32_16x16x32_bf16 v[18:21], v[162:165], v[134:137], v[18:21]
	v_mfma_f32_16x16x32_bf16 v[22:25], v[166:169], v[134:137], v[22:25]
	v_mfma_f32_16x16x32_bf16 v[26:29], v[170:173], v[134:137], v[26:29]
	v_mfma_f32_16x16x32_bf16 v[30:33], v[174:177], v[134:137], v[30:33]
	v_mfma_f32_16x16x32_bf16 v[34:37], v[162:165], v[138:141], v[34:37]
	v_mfma_f32_16x16x32_bf16 v[38:41], v[166:169], v[138:141], v[38:41]
	v_mfma_f32_16x16x32_bf16 v[42:45], v[170:173], v[138:141], v[42:45]
	v_mfma_f32_16x16x32_bf16 v[46:49], v[174:177], v[138:141], v[46:49]
	v_mfma_f32_16x16x32_bf16 v[50:53], v[162:165], v[142:145], v[50:53]
	v_mfma_f32_16x16x32_bf16 v[54:57], v[166:169], v[142:145], v[54:57]
	v_mfma_f32_16x16x32_bf16 v[58:61], v[170:173], v[142:145], v[58:61]
	v_mfma_f32_16x16x32_bf16 v[62:65], v[174:177], v[142:145], v[62:65]
	s_waitcnt lgkmcnt(0)
	v_mfma_f32_16x16x32_bf16 v[2:5], v[178:181], v[146:149], v[2:5]
	v_mfma_f32_16x16x32_bf16 v[6:9], v[182:185], v[146:149], v[6:9]
	v_mfma_f32_16x16x32_bf16 v[10:13], v[186:189], v[146:149], v[10:13]
	v_mfma_f32_16x16x32_bf16 v[14:17], v[190:193], v[146:149], v[14:17]
	v_mfma_f32_16x16x32_bf16 v[18:21], v[178:181], v[150:153], v[18:21]
	v_mfma_f32_16x16x32_bf16 v[22:25], v[182:185], v[150:153], v[22:25]
	v_mfma_f32_16x16x32_bf16 v[26:29], v[186:189], v[150:153], v[26:29]
	v_mfma_f32_16x16x32_bf16 v[30:33], v[190:193], v[150:153], v[30:33]
	v_mfma_f32_16x16x32_bf16 v[34:37], v[178:181], v[154:157], v[34:37]
	v_mfma_f32_16x16x32_bf16 v[38:41], v[182:185], v[154:157], v[38:41]
	v_mfma_f32_16x16x32_bf16 v[42:45], v[186:189], v[154:157], v[42:45]
	v_mfma_f32_16x16x32_bf16 v[46:49], v[190:193], v[154:157], v[46:49]
	v_mfma_f32_16x16x32_bf16 v[50:53], v[178:181], v[158:161], v[50:53]
	v_mfma_f32_16x16x32_bf16 v[54:57], v[182:185], v[158:161], v[54:57]
	v_mfma_f32_16x16x32_bf16 v[58:61], v[186:189], v[158:161], v[58:61]
	v_mfma_f32_16x16x32_bf16 v[62:65], v[190:193], v[158:161], v[62:65]
	s_waitcnt vmcnt(22)
	s_barrier
	s_add_u32 s66, s64, 0x480
	s_addc_u32 s67, s65, 0
	s_add_u32 s70, s68, 0x100080
	s_addc_u32 s71, s69, 0
	s_add_u32 s72, s70, 0x10000
	s_addc_u32 s73, s71, 0
	s_mov_b32 m0, s82
	s_nop 0
	global_load_lds_dwordx4 v197, s[66:67]
	s_add_i32 m0, s82, 0x2000
	s_nop 0
	global_load_lds_dwordx4 v198, s[66:67]
	s_add_i32 m0, s82, 0x4000
	s_nop 0
	global_load_lds_dwordx4 v199, s[70:71]
	s_add_i32 m0, s82, 0x6000
	s_nop 0
	global_load_lds_dwordx4 v200, s[70:71]
	s_mov_b32 m0, s85
	s_nop 0
	global_load_lds_dwordx4 v199, s[72:73]
	s_add_i32 m0, s85, 0x2000
	s_nop 0
	global_load_lds_dwordx4 v200, s[72:73]
	ds_read_b128 v[130:133], v215 offset:0
	ds_read_b128 v[134:137], v215 offset:2048
	ds_read_b128 v[138:141], v215 offset:4096
	ds_read_b128 v[142:145], v215 offset:6144
	ds_read_b128 v[162:165], v218 offset:0
	ds_read_b128 v[166:169], v218 offset:2048
	ds_read_b128 v[170:173], v218 offset:4096
	ds_read_b128 v[174:177], v218 offset:6144
	ds_read_b128 v[146:149], v215 offset:1024
	ds_read_b128 v[150:153], v215 offset:3072
	ds_read_b128 v[154:157], v215 offset:5120
	ds_read_b128 v[158:161], v215 offset:7168
	ds_read_b128 v[178:181], v218 offset:1024
	ds_read_b128 v[182:185], v218 offset:3072
	ds_read_b128 v[186:189], v218 offset:5120
	ds_read_b128 v[190:193], v218 offset:7168
	s_waitcnt lgkmcnt(8)
	v_mfma_f32_16x16x32_bf16 v[2:5], v[162:165], v[130:133], v[2:5]
	v_mfma_f32_16x16x32_bf16 v[6:9], v[166:169], v[130:133], v[6:9]
	v_mfma_f32_16x16x32_bf16 v[10:13], v[170:173], v[130:133], v[10:13]
	v_mfma_f32_16x16x32_bf16 v[14:17], v[174:177], v[130:133], v[14:17]
	v_mfma_f32_16x16x32_bf16 v[18:21], v[162:165], v[134:137], v[18:21]
	v_mfma_f32_16x16x32_bf16 v[22:25], v[166:169], v[134:137], v[22:25]
	v_mfma_f32_16x16x32_bf16 v[26:29], v[170:173], v[134:137], v[26:29]
	v_mfma_f32_16x16x32_bf16 v[30:33], v[174:177], v[134:137], v[30:33]
	v_mfma_f32_16x16x32_bf16 v[34:37], v[162:165], v[138:141], v[34:37]
	v_mfma_f32_16x16x32_bf16 v[38:41], v[166:169], v[138:141], v[38:41]
	v_mfma_f32_16x16x32_bf16 v[42:45], v[170:173], v[138:141], v[42:45]
	v_mfma_f32_16x16x32_bf16 v[46:49], v[174:177], v[138:141], v[46:49]
	v_mfma_f32_16x16x32_bf16 v[50:53], v[162:165], v[142:145], v[50:53]
	v_mfma_f32_16x16x32_bf16 v[54:57], v[166:169], v[142:145], v[54:57]
	v_mfma_f32_16x16x32_bf16 v[58:61], v[170:173], v[142:145], v[58:61]
	v_mfma_f32_16x16x32_bf16 v[62:65], v[174:177], v[142:145], v[62:65]
	s_waitcnt lgkmcnt(0)
; __device__ __forceinline__ unsigned cvtpk(float lo, float hi) { f32x2 v = {lo, hi}; bf16x2_t b = __builtin_convertvector(v, bf16x2_t); return __builtin_bit_cast(unsigned, b); }
; __device__ __forceinline__ void branch_phase(LAS unsigned char* lds, const bf16_t* __restrict__ O, const bf16_t* __restrict__ Wb, const bf16_t* __restrict__ Gt, bf16_t* __restrict__ MG, int tg, int wv) {
;     ...
; #pragma unroll
;                     for (int m = 0; m < 4; ++m)
; #pragma unroll
;                         for (int n = 0; n < 4; ++n) acc[m][n] = __builtin_amdgcn_mfma_f32_16x16x32_bf16(bfr[n], af[m], acc[m][n], 0, 0, 0);
;                 }
;                 asm volatile("s_waitcnt vmcnt(0)" ::: "memory"); __syncthreads();
;             }
; #pragma unroll
;             for (int m = 0; m < 4; ++m)
; #pragma unroll
;                 for (int n = 0; n < 4; ++n) { const u32x2 g = gv[m][n], sp = sum[m][n];
;                     const float s0_ = __builtin_bit_cast(float, sp.x << 16) + acc[m][n][0] * __builtin_bit_cast(float, g.x << 16), s1_ = __builtin_bit_cast(float, sp.x & 0xffff0000u) + acc[m][n][1] * __builtin_bit_cast(float, g.x & 0xffff0000u);
;                     const float s2_ = __builtin_bit_cast(float, sp.y << 16) + acc[m][n][2] * __builtin_bit_cast(float, g.y << 16), s3_ = __builtin_bit_cast(float, sp.y & 0xffff0000u) + acc[m][n][3] * __builtin_bit_cast(float, g.y & 0xffff0000u);
;                     sum[m][n] = (u32x2){cvtpk(s0_, s1_), cvtpk(s2_, s3_)}; }
	v_mfma_f32_16x16x32_bf16 v[2:5], v[178:181], v[146:149], v[2:5]
	v_mfma_f32_16x16x32_bf16 v[6:9], v[182:185], v[146:149], v[6:9]
	v_mfma_f32_16x16x32_bf16 v[10:13], v[186:189], v[146:149], v[10:13]
	v_mfma_f32_16x16x32_bf16 v[14:17], v[190:193], v[146:149], v[14:17]
	v_mfma_f32_16x16x32_bf16 v[18:21], v[178:181], v[150:153], v[18:21]
	v_mfma_f32_16x16x32_bf16 v[22:25], v[182:185], v[150:153], v[22:25]
	v_mfma_f32_16x16x32_bf16 v[26:29], v[186:189], v[150:153], v[26:29]
	v_mfma_f32_16x16x32_bf16 v[30:33], v[190:193], v[150:153], v[30:33]
	v_mfma_f32_16x16x32_bf16 v[34:37], v[178:181], v[154:157], v[34:37]
	v_mfma_f32_16x16x32_bf16 v[38:41], v[182:185], v[154:157], v[38:41]
	v_mfma_f32_16x16x32_bf16 v[42:45], v[186:189], v[154:157], v[42:45]
	v_mfma_f32_16x16x32_bf16 v[46:49], v[190:193], v[154:157], v[46:49]
	v_mfma_f32_16x16x32_bf16 v[50:53], v[178:181], v[158:161], v[50:53]
	v_mfma_f32_16x16x32_bf16 v[54:57], v[182:185], v[158:161], v[54:57]
	v_mfma_f32_16x16x32_bf16 v[58:61], v[186:189], v[158:161], v[58:61]
	v_mfma_f32_16x16x32_bf16 v[62:65], v[190:193], v[158:161], v[62:65]
	s_waitcnt vmcnt(6)
	s_barrier
	s_nop 7
	v_lshlrev_b32_e32 v206, 16, v98
	v_and_b32_e32 v207, 0xffff0000, v98
	v_lshlrev_b32_e32 v208, 16, v99
	v_and_b32_e32 v209, 0xffff0000, v99
	v_lshlrev_b32_e32 v210, 16, v66
	v_and_b32_e32 v211, 0xffff0000, v66
	v_lshlrev_b32_e32 v212, 16, v67
	v_and_b32_e32 v213, 0xffff0000, v67
	v_pk_fma_f32 v[210:211], v[2:3], v[206:207], v[210:211]
	v_pk_fma_f32 v[212:213], v[4:5], v[208:209], v[212:213]
	v_cvt_pk_bf16_f32 v66, v210, v211
	v_cvt_pk_bf16_f32 v67, v212, v213
	v_lshlrev_b32_e32 v206, 16, v100
	v_and_b32_e32 v207, 0xffff0000, v100
	v_lshlrev_b32_e32 v208, 16, v101
	v_and_b32_e32 v209, 0xffff0000, v101
	v_lshlrev_b32_e32 v210, 16, v68
	v_and_b32_e32 v211, 0xffff0000, v68
	v_lshlrev_b32_e32 v212, 16, v69
	v_and_b32_e32 v213, 0xffff0000, v69
	v_pk_fma_f32 v[210:211], v[6:7], v[206:207], v[210:211]
	v_pk_fma_f32 v[212:213], v[8:9], v[208:209], v[212:213]
	v_cvt_pk_bf16_f32 v68, v210, v211
	v_cvt_pk_bf16_f32 v69, v212, v213
	v_lshlrev_b32_e32 v206, 16, v102
	v_and_b32_e32 v207, 0xffff0000, v102
	v_lshlrev_b32_e32 v208, 16, v103
	v_and_b32_e32 v209, 0xffff0000, v103
	v_lshlrev_b32_e32 v210, 16, v70
	v_and_b32_e32 v211, 0xffff0000, v70
	v_lshlrev_b32_e32 v212, 16, v71
	v_and_b32_e32 v213, 0xffff0000, v71
	v_pk_fma_f32 v[210:211], v[10:11], v[206:207], v[210:211]
	v_pk_fma_f32 v[212:213], v[12:13], v[208:209], v[212:213]
	v_cvt_pk_bf16_f32 v70, v210, v211
	v_cvt_pk_bf16_f32 v71, v212, v213
	v_lshlrev_b32_e32 v206, 16, v104
	v_and_b32_e32 v207, 0xffff0000, v104
	v_lshlrev_b32_e32 v208, 16, v105
	v_and_b32_e32 v209, 0xffff0000, v105
	v_lshlrev_b32_e32 v210, 16, v72
	v_and_b32_e32 v211, 0xffff0000, v72
	v_lshlrev_b32_e32 v212, 16, v73
	v_and_b32_e32 v213, 0xffff0000, v73
	v_pk_fma_f32 v[210:211], v[14:15], v[206:207], v[210:211]
	v_pk_fma_f32 v[212:213], v[16:17], v[208:209], v[212:213]
	v_cvt_pk_bf16_f32 v72, v210, v211
	v_cvt_pk_bf16_f32 v73, v212, v213
	v_lshlrev_b32_e32 v206, 16, v106
	v_and_b32_e32 v207, 0xffff0000, v106
	v_lshlrev_b32_e32 v208, 16, v107
	v_and_b32_e32 v209, 0xffff0000, v107
	v_lshlrev_b32_e32 v210, 16, v74
	v_and_b32_e32 v211, 0xffff0000, v74
	v_lshlrev_b32_e32 v212, 16, v75
	v_and_b32_e32 v213, 0xffff0000, v75
	v_pk_fma_f32 v[210:211], v[18:19], v[206:207], v[210:211]
	v_pk_fma_f32 v[212:213], v[20:21], v[208:209], v[212:213]
	v_cvt_pk_bf16_f32 v74, v210, v211
	v_cvt_pk_bf16_f32 v75, v212, v213
	v_lshlrev_b32_e32 v206, 16, v108
	v_and_b32_e32 v207, 0xffff0000, v108
	v_lshlrev_b32_e32 v208, 16, v109
	v_and_b32_e32 v209, 0xffff0000, v109
	v_lshlrev_b32_e32 v210, 16, v76
	v_and_b32_e32 v211, 0xffff0000, v76
	v_lshlrev_b32_e32 v212, 16, v77
	v_and_b32_e32 v213, 0xffff0000, v77
	v_pk_fma_f32 v[210:211], v[22:23], v[206:207], v[210:211]
	v_pk_fma_f32 v[212:213], v[24:25], v[208:209], v[212:213]
	v_cvt_pk_bf16_f32 v76, v210, v211
	v_cvt_pk_bf16_f32 v77, v212, v213
	v_lshlrev_b32_e32 v206, 16, v110
	v_and_b32_e32 v207, 0xffff0000, v110
	v_lshlrev_b32_e32 v208, 16, v111
	v_and_b32_e32 v209, 0xffff0000, v111
	v_lshlrev_b32_e32 v210, 16, v78
	v_and_b32_e32 v211, 0xffff0000, v78
	v_lshlrev_b32_e32 v212, 16, v79
	v_and_b32_e32 v213, 0xffff0000, v79
	v_pk_fma_f32 v[210:211], v[26:27], v[206:207], v[210:211]
	v_pk_fma_f32 v[212:213], v[28:29], v[208:209], v[212:213]
	v_cvt_pk_bf16_f32 v78, v210, v211
	v_cvt_pk_bf16_f32 v79, v212, v213
	v_lshlrev_b32_e32 v206, 16, v112
	v_and_b32_e32 v207, 0xffff0000, v112
	v_lshlrev_b32_e32 v208, 16, v113
	v_and_b32_e32 v209, 0xffff0000, v113
	v_lshlrev_b32_e32 v210, 16, v80
	v_and_b32_e32 v211, 0xffff0000, v80
	v_lshlrev_b32_e32 v212, 16, v81
	v_and_b32_e32 v213, 0xffff0000, v81
	v_pk_fma_f32 v[210:211], v[30:31], v[206:207], v[210:211]
	v_pk_fma_f32 v[212:213], v[32:33], v[208:209], v[212:213]
	v_cvt_pk_bf16_f32 v80, v210, v211
	v_cvt_pk_bf16_f32 v81, v212, v213
	v_lshlrev_b32_e32 v206, 16, v114
	v_and_b32_e32 v207, 0xffff0000, v114
	v_lshlrev_b32_e32 v208, 16, v115
	v_and_b32_e32 v209, 0xffff0000, v115
	v_lshlrev_b32_e32 v210, 16, v82
	v_and_b32_e32 v211, 0xffff0000, v82
	v_lshlrev_b32_e32 v212, 16, v83
	v_and_b32_e32 v213, 0xffff0000, v83
	v_pk_fma_f32 v[210:211], v[34:35], v[206:207], v[210:211]
	v_pk_fma_f32 v[212:213], v[36:37], v[208:209], v[212:213]
	v_cvt_pk_bf16_f32 v82, v210, v211
	v_cvt_pk_bf16_f32 v83, v212, v213
	v_lshlrev_b32_e32 v206, 16, v116
	v_and_b32_e32 v207, 0xffff0000, v116
	v_lshlrev_b32_e32 v208, 16, v117
	v_and_b32_e32 v209, 0xffff0000, v117
	v_lshlrev_b32_e32 v210, 16, v84
	v_and_b32_e32 v211, 0xffff0000, v84
	v_lshlrev_b32_e32 v212, 16, v85
	v_and_b32_e32 v213, 0xffff0000, v85
; __device__ __forceinline__ void branch_phase(LAS unsigned char* lds, const bf16_t* __restrict__ O, const bf16_t* __restrict__ Wb, const bf16_t* __restrict__ Gt, bf16_t* __restrict__ MG, int tg, int wv) {
;     ...
;         BR_LOAD(0, 0);
;         asm volatile("s_waitcnt vmcnt(0)" ::: "memory"); __syncthreads();
;         for (int j = 0; j < 4; ++j) {
;             u32x2 gv[4][4];
;             f32x4 acc[4][4];
; #pragma unroll
;             for (int m = 0; m < 4; ++m)
; #pragma unroll
;                 for (int n = 0; n < 4; ++n) acc[m][n] = (f32x4){0.f, 0.f, 0.f, 0.f};
;             for (int kc = 0; kc < 4; ++kc) {
;                 const int c = j * 4 + kc;
;                 if (c + 1 < 16) BR_LOAD(c + 1, (c + 1) & 1);
;                 if (kc == 3) {
;                     const bf16_t* gp = Gt + (size_t)(rt * 128 + wm * 64 + fr) * ZC + j * 1024 + ct * 256 + wn * 64 + 4 * fq;
; #pragma unroll
;                     for (int m = 0; m < 4; ++m)
; #pragma unroll
;                         for (int n = 0; n < 4; ++n) gv[m][n] = *(const u32x2*)(gp + (size_t)m * 16 * ZC + n * 16);
;                 }
;                 LAS const unsigned char* st = lds + (c & 1) * STG;
; #pragma unroll
;                 for (int k = 0; k < 2; ++k) {
;                     __builtin_amdgcn_sched_barrier(0);
;                     bf16x8 af[4], bfr[4];
; #pragma unroll
;                     for (int m = 0; m < 4; ++m) af[m] = *(LAS const bf16x8*)(st + aoff + m * 2048 + k * 1024);
; #pragma unroll
;                     for (int n = 0; n < 4; ++n) bfr[n] = *(LAS const bf16x8*)(st + boff + n * 2048 + k * 1024);
; #pragma unroll
;     ...
; #pragma unroll
;             for (int m = 0; m < 4; ++m)
; #pragma unroll
;                 for (int n = 0; n < 4; ++n) { const u32x2 g = gv[m][n], sp = sum[m][n];
;                     const float s0_ = __builtin_bit_cast(float, sp.x << 16) + acc[m][n][0] * __builtin_bit_cast(float, g.x << 16), s1_ = __builtin_bit_cast(float, sp.x & 0xffff0000u) + acc[m][n][1] * __builtin_bit_cast(float, g.x & 0xffff0000u);
;                     const float s2_ = __builtin_bit_cast(float, sp.y << 16) + acc[m][n][2] * __builtin_bit_cast(float, g.y << 16), s3_ = __builtin_bit_cast(float, sp.y & 0xffff0000u) + acc[m][n][3] * __builtin_bit_cast(float, g.y & 0xffff0000u);
;                     sum[m][n] = (u32x2){cvtpk(s0_, s1_), cvtpk(s2_, s3_)}; }
	v_pk_fma_f32 v[210:211], v[38:39], v[206:207], v[210:211]
	v_pk_fma_f32 v[212:213], v[40:41], v[208:209], v[212:213]
	v_cvt_pk_bf16_f32 v84, v210, v211
	v_cvt_pk_bf16_f32 v85, v212, v213
	v_lshlrev_b32_e32 v206, 16, v118
	v_and_b32_e32 v207, 0xffff0000, v118
	v_lshlrev_b32_e32 v208, 16, v119
	v_and_b32_e32 v209, 0xffff0000, v119
	v_lshlrev_b32_e32 v210, 16, v86
	v_and_b32_e32 v211, 0xffff0000, v86
	v_lshlrev_b32_e32 v212, 16, v87
	v_and_b32_e32 v213, 0xffff0000, v87
	v_pk_fma_f32 v[210:211], v[42:43], v[206:207], v[210:211]
	v_pk_fma_f32 v[212:213], v[44:45], v[208:209], v[212:213]
	v_cvt_pk_bf16_f32 v86, v210, v211
	v_cvt_pk_bf16_f32 v87, v212, v213
	v_lshlrev_b32_e32 v206, 16, v120
	v_and_b32_e32 v207, 0xffff0000, v120
	v_lshlrev_b32_e32 v208, 16, v121
	v_and_b32_e32 v209, 0xffff0000, v121
	v_lshlrev_b32_e32 v210, 16, v88
	v_and_b32_e32 v211, 0xffff0000, v88
	v_lshlrev_b32_e32 v212, 16, v89
	v_and_b32_e32 v213, 0xffff0000, v89
	v_pk_fma_f32 v[210:211], v[46:47], v[206:207], v[210:211]
	v_pk_fma_f32 v[212:213], v[48:49], v[208:209], v[212:213]
	v_cvt_pk_bf16_f32 v88, v210, v211
	v_cvt_pk_bf16_f32 v89, v212, v213
	v_lshlrev_b32_e32 v206, 16, v122
	v_and_b32_e32 v207, 0xffff0000, v122
	v_lshlrev_b32_e32 v208, 16, v123
	v_and_b32_e32 v209, 0xffff0000, v123
	v_lshlrev_b32_e32 v210, 16, v90
	v_and_b32_e32 v211, 0xffff0000, v90
	v_lshlrev_b32_e32 v212, 16, v91
	v_and_b32_e32 v213, 0xffff0000, v91
	v_pk_fma_f32 v[210:211], v[50:51], v[206:207], v[210:211]
	v_pk_fma_f32 v[212:213], v[52:53], v[208:209], v[212:213]
	v_cvt_pk_bf16_f32 v90, v210, v211
	v_cvt_pk_bf16_f32 v91, v212, v213
	v_lshlrev_b32_e32 v206, 16, v124
	v_and_b32_e32 v207, 0xffff0000, v124
	v_lshlrev_b32_e32 v208, 16, v125
	v_and_b32_e32 v209, 0xffff0000, v125
	v_lshlrev_b32_e32 v210, 16, v92
	v_and_b32_e32 v211, 0xffff0000, v92
	v_lshlrev_b32_e32 v212, 16, v93
	v_and_b32_e32 v213, 0xffff0000, v93
	v_pk_fma_f32 v[210:211], v[54:55], v[206:207], v[210:211]
	v_pk_fma_f32 v[212:213], v[56:57], v[208:209], v[212:213]
	v_cvt_pk_bf16_f32 v92, v210, v211
	v_cvt_pk_bf16_f32 v93, v212, v213
	v_lshlrev_b32_e32 v206, 16, v126
	v_and_b32_e32 v207, 0xffff0000, v126
	v_lshlrev_b32_e32 v208, 16, v127
	v_and_b32_e32 v209, 0xffff0000, v127
	v_lshlrev_b32_e32 v210, 16, v94
	v_and_b32_e32 v211, 0xffff0000, v94
	v_lshlrev_b32_e32 v212, 16, v95
	v_and_b32_e32 v213, 0xffff0000, v95
	v_pk_fma_f32 v[210:211], v[58:59], v[206:207], v[210:211]
	v_pk_fma_f32 v[212:213], v[60:61], v[208:209], v[212:213]
	v_cvt_pk_bf16_f32 v94, v210, v211
	v_cvt_pk_bf16_f32 v95, v212, v213
	v_lshlrev_b32_e32 v206, 16, v128
	v_and_b32_e32 v207, 0xffff0000, v128
	v_lshlrev_b32_e32 v208, 16, v129
	v_and_b32_e32 v209, 0xffff0000, v129
	v_lshlrev_b32_e32 v210, 16, v96
	v_and_b32_e32 v211, 0xffff0000, v96
	v_lshlrev_b32_e32 v212, 16, v97
	v_and_b32_e32 v213, 0xffff0000, v97
	v_pk_fma_f32 v[210:211], v[62:63], v[206:207], v[210:211]
	v_pk_fma_f32 v[212:213], v[64:65], v[208:209], v[212:213]
	v_cvt_pk_bf16_f32 v96, v210, v211
	v_cvt_pk_bf16_f32 v97, v212, v213
	s_add_u32 s66, s64, 0x500
	s_addc_u32 s67, s65, 0
	s_add_u32 s70, s68, 0x100100
	s_addc_u32 s71, s69, 0
	s_add_u32 s72, s70, 0x10000
	s_addc_u32 s73, s71, 0
	s_mov_b32 m0, s83
	s_nop 0
	global_load_lds_dwordx4 v197, s[66:67]
	s_add_i32 m0, s83, 0x2000
	s_nop 0
	global_load_lds_dwordx4 v198, s[66:67]
	s_add_i32 m0, s83, 0x4000
	s_nop 0
	global_load_lds_dwordx4 v199, s[70:71]
	s_add_i32 m0, s83, 0x6000
	s_nop 0
	global_load_lds_dwordx4 v200, s[70:71]
	s_mov_b32 m0, s60
	s_nop 0
	global_load_lds_dwordx4 v199, s[72:73]
	s_add_i32 m0, s60, 0x2000
	s_nop 0
	global_load_lds_dwordx4 v200, s[72:73]
	ds_read_b128 v[130:133], v216 offset:0
	ds_read_b128 v[134:137], v216 offset:2048
	ds_read_b128 v[138:141], v216 offset:4096
	ds_read_b128 v[142:145], v216 offset:6144
	ds_read_b128 v[162:165], v219 offset:0
	ds_read_b128 v[166:169], v219 offset:2048
	ds_read_b128 v[170:173], v219 offset:4096
	ds_read_b128 v[174:177], v219 offset:6144
	ds_read_b128 v[146:149], v216 offset:1024
	ds_read_b128 v[150:153], v216 offset:3072
	ds_read_b128 v[154:157], v216 offset:5120
	ds_read_b128 v[158:161], v216 offset:7168
	ds_read_b128 v[178:181], v219 offset:1024
	ds_read_b128 v[182:185], v219 offset:3072
	ds_read_b128 v[186:189], v219 offset:5120
	ds_read_b128 v[190:193], v219 offset:7168
	s_waitcnt lgkmcnt(8)
	v_mfma_f32_16x16x32_bf16 v[2:5], v[162:165], v[130:133], 0
	v_mfma_f32_16x16x32_bf16 v[6:9], v[166:169], v[130:133], 0
	v_mfma_f32_16x16x32_bf16 v[10:13], v[170:173], v[130:133], 0
	v_mfma_f32_16x16x32_bf16 v[14:17], v[174:177], v[130:133], 0
	v_mfma_f32_16x16x32_bf16 v[18:21], v[162:165], v[134:137], 0
	v_mfma_f32_16x16x32_bf16 v[22:25], v[166:169], v[134:137], 0
	v_mfma_f32_16x16x32_bf16 v[26:29], v[170:173], v[134:137], 0
	v_mfma_f32_16x16x32_bf16 v[30:33], v[174:177], v[134:137], 0
	v_mfma_f32_16x16x32_bf16 v[34:37], v[162:165], v[138:141], 0
	v_mfma_f32_16x16x32_bf16 v[38:41], v[166:169], v[138:141], 0
	v_mfma_f32_16x16x32_bf16 v[42:45], v[170:173], v[138:141], 0
	v_mfma_f32_16x16x32_bf16 v[46:49], v[174:177], v[138:141], 0
	v_mfma_f32_16x16x32_bf16 v[50:53], v[162:165], v[142:145], 0
	v_mfma_f32_16x16x32_bf16 v[54:57], v[166:169], v[142:145], 0
	v_mfma_f32_16x16x32_bf16 v[58:61], v[170:173], v[142:145], 0
	v_mfma_f32_16x16x32_bf16 v[62:65], v[174:177], v[142:145], 0
	s_waitcnt lgkmcnt(0)
	v_mfma_f32_16x16x32_bf16 v[2:5], v[178:181], v[146:149], v[2:5]
	v_mfma_f32_16x16x32_bf16 v[6:9], v[182:185], v[146:149], v[6:9]
	v_mfma_f32_16x16x32_bf16 v[10:13], v[186:189], v[146:149], v[10:13]
	v_mfma_f32_16x16x32_bf16 v[14:17], v[190:193], v[146:149], v[14:17]
	v_mfma_f32_16x16x32_bf16 v[18:21], v[178:181], v[150:153], v[18:21]
	v_mfma_f32_16x16x32_bf16 v[22:25], v[182:185], v[150:153], v[22:25]
	v_mfma_f32_16x16x32_bf16 v[26:29], v[186:189], v[150:153], v[26:29]
	v_mfma_f32_16x16x32_bf16 v[30:33], v[190:193], v[150:153], v[30:33]
	v_mfma_f32_16x16x32_bf16 v[34:37], v[178:181], v[154:157], v[34:37]
	v_mfma_f32_16x16x32_bf16 v[38:41], v[182:185], v[154:157], v[38:41]
	v_mfma_f32_16x16x32_bf16 v[42:45], v[186:189], v[154:157], v[42:45]
	v_mfma_f32_16x16x32_bf16 v[46:49], v[190:193], v[154:157], v[46:49]
	v_mfma_f32_16x16x32_bf16 v[50:53], v[178:181], v[158:161], v[50:53]
	v_mfma_f32_16x16x32_bf16 v[54:57], v[182:185], v[158:161], v[54:57]
	v_mfma_f32_16x16x32_bf16 v[58:61], v[186:189], v[158:161], v[58:61]
	v_mfma_f32_16x16x32_bf16 v[62:65], v[190:193], v[158:161], v[62:65]
	s_waitcnt vmcnt(6)
	s_barrier
; #define LAS __attribute__((address_space(3)))
; __device__ __forceinline__ void branch_phase(LAS unsigned char* lds, const bf16_t* __restrict__ O, const bf16_t* __restrict__ Wb, const bf16_t* __restrict__ Gt, bf16_t* __restrict__ MG, int tg, int wv) {
;     ...
;         BR_LOAD(0, 0);
;         asm volatile("s_waitcnt vmcnt(0)" ::: "memory"); __syncthreads();
;         for (int j = 0; j < 4; ++j) {
;             u32x2 gv[4][4];
;             f32x4 acc[4][4];
; #pragma unroll
;             for (int m = 0; m < 4; ++m)
; #pragma unroll
;                 for (int n = 0; n < 4; ++n) acc[m][n] = (f32x4){0.f, 0.f, 0.f, 0.f};
;             for (int kc = 0; kc < 4; ++kc) {
;                 const int c = j * 4 + kc;
;                 if (c + 1 < 16) BR_LOAD(c + 1, (c + 1) & 1);
;                 if (kc == 3) {
;                     const bf16_t* gp = Gt + (size_t)(rt * 128 + wm * 64 + fr) * ZC + j * 1024 + ct * 256 + wn * 64 + 4 * fq;
; #pragma unroll
;                     for (int m = 0; m < 4; ++m)
; #pragma unroll
;                         for (int n = 0; n < 4; ++n) gv[m][n] = *(const u32x2*)(gp + (size_t)m * 16 * ZC + n * 16);
;                 }
;                 LAS const unsigned char* st = lds + (c & 1) * STG;
; #pragma unroll
;                 for (int k = 0; k < 2; ++k) {
;                     __builtin_amdgcn_sched_barrier(0);
;                     bf16x8 af[4], bfr[4];
; #pragma unroll
;                     for (int m = 0; m < 4; ++m) af[m] = *(LAS const bf16x8*)(st + aoff + m * 2048 + k * 1024);
; #pragma unroll
;                     for (int n = 0; n < 4; ++n) bfr[n] = *(LAS const bf16x8*)(st + boff + n * 2048 + k * 1024);
; #pragma unroll
;                     for (int m = 0; m < 4; ++m)
; #pragma unroll
;                         for (int n = 0; n < 4; ++n) acc[m][n] = __builtin_amdgcn_mfma_f32_16x16x32_bf16(bfr[n], af[m], acc[m][n], 0, 0, 0);
;                 }
;                 asm volatile("s_waitcnt vmcnt(0)" ::: "memory"); __syncthreads();
	s_add_u32 s66, s64, 0x580
	s_addc_u32 s67, s65, 0
	s_add_u32 s70, s68, 0x100180
	s_addc_u32 s71, s69, 0
	s_add_u32 s72, s70, 0x10000
	s_addc_u32 s73, s71, 0
	s_mov_b32 m0, s84
	s_nop 0
	global_load_lds_dwordx4 v197, s[66:67]
	s_add_i32 m0, s84, 0x2000
	s_nop 0
	global_load_lds_dwordx4 v198, s[66:67]
	s_add_i32 m0, s84, 0x4000
	s_nop 0
	global_load_lds_dwordx4 v199, s[70:71]
	s_add_i32 m0, s84, 0x6000
	s_nop 0
	global_load_lds_dwordx4 v200, s[70:71]
	s_mov_b32 m0, s61
	s_nop 0
	global_load_lds_dwordx4 v199, s[72:73]
	s_add_i32 m0, s61, 0x2000
	s_nop 0
	global_load_lds_dwordx4 v200, s[72:73]
	s_add_u32 s80, s74, 0x1000
	s_addc_u32 s81, s75, 0
	global_load_dwordx2 v[98:99], v204, s[80:81] offset:0
	global_load_dwordx2 v[100:101], v204, s[80:81] offset:32
	global_load_dwordx2 v[102:103], v204, s[80:81] offset:64
	global_load_dwordx2 v[104:105], v204, s[80:81] offset:96
	s_add_u32 s80, s80, 0x20000
	s_addc_u32 s81, s81, 0
	global_load_dwordx2 v[106:107], v204, s[80:81] offset:0
	global_load_dwordx2 v[108:109], v204, s[80:81] offset:32
	global_load_dwordx2 v[110:111], v204, s[80:81] offset:64
	global_load_dwordx2 v[112:113], v204, s[80:81] offset:96
	s_add_u32 s80, s80, 0x20000
	s_addc_u32 s81, s81, 0
	global_load_dwordx2 v[114:115], v204, s[80:81] offset:0
	global_load_dwordx2 v[116:117], v204, s[80:81] offset:32
	global_load_dwordx2 v[118:119], v204, s[80:81] offset:64
	global_load_dwordx2 v[120:121], v204, s[80:81] offset:96
	s_add_u32 s80, s80, 0x20000
	s_addc_u32 s81, s81, 0
	global_load_dwordx2 v[122:123], v204, s[80:81] offset:0
	global_load_dwordx2 v[124:125], v204, s[80:81] offset:32
	global_load_dwordx2 v[126:127], v204, s[80:81] offset:64
	global_load_dwordx2 v[128:129], v204, s[80:81] offset:96
	ds_read_b128 v[130:133], v214 offset:0
	ds_read_b128 v[134:137], v214 offset:2048
	ds_read_b128 v[138:141], v214 offset:4096
	ds_read_b128 v[142:145], v214 offset:6144
	ds_read_b128 v[162:165], v217 offset:0
	ds_read_b128 v[166:169], v217 offset:2048
	ds_read_b128 v[170:173], v217 offset:4096
	ds_read_b128 v[174:177], v217 offset:6144
	ds_read_b128 v[146:149], v214 offset:1024
	ds_read_b128 v[150:153], v214 offset:3072
	ds_read_b128 v[154:157], v214 offset:5120
	ds_read_b128 v[158:161], v214 offset:7168
	ds_read_b128 v[178:181], v217 offset:1024
	ds_read_b128 v[182:185], v217 offset:3072
	ds_read_b128 v[186:189], v217 offset:5120
	ds_read_b128 v[190:193], v217 offset:7168
	s_waitcnt lgkmcnt(8)
	v_mfma_f32_16x16x32_bf16 v[2:5], v[162:165], v[130:133], v[2:5]
	v_mfma_f32_16x16x32_bf16 v[6:9], v[166:169], v[130:133], v[6:9]
	v_mfma_f32_16x16x32_bf16 v[10:13], v[170:173], v[130:133], v[10:13]
	v_mfma_f32_16x16x32_bf16 v[14:17], v[174:177], v[130:133], v[14:17]
	v_mfma_f32_16x16x32_bf16 v[18:21], v[162:165], v[134:137], v[18:21]
	v_mfma_f32_16x16x32_bf16 v[22:25], v[166:169], v[134:137], v[22:25]
	v_mfma_f32_16x16x32_bf16 v[26:29], v[170:173], v[134:137], v[26:29]
	v_mfma_f32_16x16x32_bf16 v[30:33], v[174:177], v[134:137], v[30:33]
	v_mfma_f32_16x16x32_bf16 v[34:37], v[162:165], v[138:141], v[34:37]
	v_mfma_f32_16x16x32_bf16 v[38:41], v[166:169], v[138:141], v[38:41]
	v_mfma_f32_16x16x32_bf16 v[42:45], v[170:173], v[138:141], v[42:45]
	v_mfma_f32_16x16x32_bf16 v[46:49], v[174:177], v[138:141], v[46:49]
	v_mfma_f32_16x16x32_bf16 v[50:53], v[162:165], v[142:145], v[50:53]
	v_mfma_f32_16x16x32_bf16 v[54:57], v[166:169], v[142:145], v[54:57]
	v_mfma_f32_16x16x32_bf16 v[58:61], v[170:173], v[142:145], v[58:61]
	v_mfma_f32_16x16x32_bf16 v[62:65], v[174:177], v[142:145], v[62:65]
	s_waitcnt lgkmcnt(0)
	v_mfma_f32_16x16x32_bf16 v[2:5], v[178:181], v[146:149], v[2:5]
	v_mfma_f32_16x16x32_bf16 v[6:9], v[182:185], v[146:149], v[6:9]
	v_mfma_f32_16x16x32_bf16 v[10:13], v[186:189], v[146:149], v[10:13]
	v_mfma_f32_16x16x32_bf16 v[14:17], v[190:193], v[146:149], v[14:17]
	v_mfma_f32_16x16x32_bf16 v[18:21], v[178:181], v[150:153], v[18:21]
	v_mfma_f32_16x16x32_bf16 v[22:25], v[182:185], v[150:153], v[22:25]
	v_mfma_f32_16x16x32_bf16 v[26:29], v[186:189], v[150:153], v[26:29]
	v_mfma_f32_16x16x32_bf16 v[30:33], v[190:193], v[150:153], v[30:33]
	v_mfma_f32_16x16x32_bf16 v[34:37], v[178:181], v[154:157], v[34:37]
	v_mfma_f32_16x16x32_bf16 v[38:41], v[182:185], v[154:157], v[38:41]
	v_mfma_f32_16x16x32_bf16 v[42:45], v[186:189], v[154:157], v[42:45]
	v_mfma_f32_16x16x32_bf16 v[46:49], v[190:193], v[154:157], v[46:49]
	v_mfma_f32_16x16x32_bf16 v[50:53], v[178:181], v[158:161], v[50:53]
	v_mfma_f32_16x16x32_bf16 v[54:57], v[182:185], v[158:161], v[54:57]
	v_mfma_f32_16x16x32_bf16 v[58:61], v[186:189], v[158:161], v[58:61]
	v_mfma_f32_16x16x32_bf16 v[62:65], v[190:193], v[158:161], v[62:65]
	s_waitcnt vmcnt(22)
	s_barrier
; #define LAS __attribute__((address_space(3)))
; __device__ __forceinline__ void branch_phase(LAS unsigned char* lds, const bf16_t* __restrict__ O, const bf16_t* __restrict__ Wb, const bf16_t* __restrict__ Gt, bf16_t* __restrict__ MG, int tg, int wv) {
;     ...
;         BR_LOAD(0, 0);
;         asm volatile("s_waitcnt vmcnt(0)" ::: "memory"); __syncthreads();
;         for (int j = 0; j < 4; ++j) {
;             u32x2 gv[4][4];
;             f32x4 acc[4][4];
; #pragma unroll
;             for (int m = 0; m < 4; ++m)
; #pragma unroll
;                 for (int n = 0; n < 4; ++n) acc[m][n] = (f32x4){0.f, 0.f, 0.f, 0.f};
;             for (int kc = 0; kc < 4; ++kc) {
;                 const int c = j * 4 + kc;
;                 if (c + 1 < 16) BR_LOAD(c + 1, (c + 1) & 1);
;                 if (kc == 3) {
;                     const bf16_t* gp = Gt + (size_t)(rt * 128 + wm * 64 + fr) * ZC + j * 1024 + ct * 256 + wn * 64 + 4 * fq;
; #pragma unroll
;                     for (int m = 0; m < 4; ++m)
; #pragma unroll
;                         for (int n = 0; n < 4; ++n) gv[m][n] = *(const u32x2*)(gp + (size_t)m * 16 * ZC + n * 16);
;                 }
;                 LAS const unsigned char* st = lds + (c & 1) * STG;
; #pragma unroll
;                 for (int k = 0; k < 2; ++k) {
;                     __builtin_amdgcn_sched_barrier(0);
;                     bf16x8 af[4], bfr[4];
; #pragma unroll
;                     for (int m = 0; m < 4; ++m) af[m] = *(LAS const bf16x8*)(st + aoff + m * 2048 + k * 1024);
; #pragma unroll
;                     for (int n = 0; n < 4; ++n) bfr[n] = *(LAS const bf16x8*)(st + boff + n * 2048 + k * 1024);
; #pragma unroll
;                     for (int m = 0; m < 4; ++m)
; #pragma unroll
;                         for (int n = 0; n < 4; ++n) acc[m][n] = __builtin_amdgcn_mfma_f32_16x16x32_bf16(bfr[n], af[m], acc[m][n], 0, 0, 0);
;                 }
;                 asm volatile("s_waitcnt vmcnt(0)" ::: "memory"); __syncthreads();
	s_add_u32 s66, s64, 0x600
	s_addc_u32 s67, s65, 0
	s_add_u32 s70, s68, 0x180000
	s_addc_u32 s71, s69, 0
	s_add_u32 s72, s70, 0x10000
	s_addc_u32 s73, s71, 0
	s_mov_b32 m0, s82
	s_nop 0
	global_load_lds_dwordx4 v197, s[66:67]
	s_add_i32 m0, s82, 0x2000
	s_nop 0
	global_load_lds_dwordx4 v198, s[66:67]
	s_add_i32 m0, s82, 0x4000
	s_nop 0
	global_load_lds_dwordx4 v199, s[70:71]
	s_add_i32 m0, s82, 0x6000
	s_nop 0
	global_load_lds_dwordx4 v200, s[70:71]
	s_mov_b32 m0, s85
	s_nop 0
	global_load_lds_dwordx4 v199, s[72:73]
	s_add_i32 m0, s85, 0x2000
	s_nop 0
	global_load_lds_dwordx4 v200, s[72:73]
	ds_read_b128 v[130:133], v215 offset:0
	ds_read_b128 v[134:137], v215 offset:2048
	ds_read_b128 v[138:141], v215 offset:4096
	ds_read_b128 v[142:145], v215 offset:6144
	ds_read_b128 v[162:165], v218 offset:0
	ds_read_b128 v[166:169], v218 offset:2048
	ds_read_b128 v[170:173], v218 offset:4096
	ds_read_b128 v[174:177], v218 offset:6144
	ds_read_b128 v[146:149], v215 offset:1024
	ds_read_b128 v[150:153], v215 offset:3072
	ds_read_b128 v[154:157], v215 offset:5120
	ds_read_b128 v[158:161], v215 offset:7168
	ds_read_b128 v[178:181], v218 offset:1024
	ds_read_b128 v[182:185], v218 offset:3072
	ds_read_b128 v[186:189], v218 offset:5120
	ds_read_b128 v[190:193], v218 offset:7168
	s_waitcnt lgkmcnt(8)
	v_mfma_f32_16x16x32_bf16 v[2:5], v[162:165], v[130:133], v[2:5]
	v_mfma_f32_16x16x32_bf16 v[6:9], v[166:169], v[130:133], v[6:9]
	v_mfma_f32_16x16x32_bf16 v[10:13], v[170:173], v[130:133], v[10:13]
	v_mfma_f32_16x16x32_bf16 v[14:17], v[174:177], v[130:133], v[14:17]
	v_mfma_f32_16x16x32_bf16 v[18:21], v[162:165], v[134:137], v[18:21]
	v_mfma_f32_16x16x32_bf16 v[22:25], v[166:169], v[134:137], v[22:25]
	v_mfma_f32_16x16x32_bf16 v[26:29], v[170:173], v[134:137], v[26:29]
	v_mfma_f32_16x16x32_bf16 v[30:33], v[174:177], v[134:137], v[30:33]
	v_mfma_f32_16x16x32_bf16 v[34:37], v[162:165], v[138:141], v[34:37]
	v_mfma_f32_16x16x32_bf16 v[38:41], v[166:169], v[138:141], v[38:41]
	v_mfma_f32_16x16x32_bf16 v[42:45], v[170:173], v[138:141], v[42:45]
	v_mfma_f32_16x16x32_bf16 v[46:49], v[174:177], v[138:141], v[46:49]
	v_mfma_f32_16x16x32_bf16 v[50:53], v[162:165], v[142:145], v[50:53]
	v_mfma_f32_16x16x32_bf16 v[54:57], v[166:169], v[142:145], v[54:57]
	v_mfma_f32_16x16x32_bf16 v[58:61], v[170:173], v[142:145], v[58:61]
	v_mfma_f32_16x16x32_bf16 v[62:65], v[174:177], v[142:145], v[62:65]
	s_waitcnt lgkmcnt(0)
	v_mfma_f32_16x16x32_bf16 v[2:5], v[178:181], v[146:149], v[2:5]
	v_mfma_f32_16x16x32_bf16 v[6:9], v[182:185], v[146:149], v[6:9]
	v_mfma_f32_16x16x32_bf16 v[10:13], v[186:189], v[146:149], v[10:13]
	v_mfma_f32_16x16x32_bf16 v[14:17], v[190:193], v[146:149], v[14:17]
	v_mfma_f32_16x16x32_bf16 v[18:21], v[178:181], v[150:153], v[18:21]
	v_mfma_f32_16x16x32_bf16 v[22:25], v[182:185], v[150:153], v[22:25]
	v_mfma_f32_16x16x32_bf16 v[26:29], v[186:189], v[150:153], v[26:29]
	v_mfma_f32_16x16x32_bf16 v[30:33], v[190:193], v[150:153], v[30:33]
	v_mfma_f32_16x16x32_bf16 v[34:37], v[178:181], v[154:157], v[34:37]
	v_mfma_f32_16x16x32_bf16 v[38:41], v[182:185], v[154:157], v[38:41]
	v_mfma_f32_16x16x32_bf16 v[42:45], v[186:189], v[154:157], v[42:45]
	v_mfma_f32_16x16x32_bf16 v[46:49], v[190:193], v[154:157], v[46:49]
	v_mfma_f32_16x16x32_bf16 v[50:53], v[178:181], v[158:161], v[50:53]
	v_mfma_f32_16x16x32_bf16 v[54:57], v[182:185], v[158:161], v[54:57]
	v_mfma_f32_16x16x32_bf16 v[58:61], v[186:189], v[158:161], v[58:61]
	v_mfma_f32_16x16x32_bf16 v[62:65], v[190:193], v[158:161], v[62:65]
	s_waitcnt vmcnt(22)
	s_barrier
	s_add_u32 s66, s64, 0x680
	s_addc_u32 s67, s65, 0
	s_add_u32 s70, s68, 0x180080
	s_addc_u32 s71, s69, 0
	s_add_u32 s72, s70, 0x10000
	s_addc_u32 s73, s71, 0
	s_mov_b32 m0, s83
	s_nop 0
	global_load_lds_dwordx4 v197, s[66:67]
	s_add_i32 m0, s83, 0x2000
	s_nop 0
	global_load_lds_dwordx4 v198, s[66:67]
	s_add_i32 m0, s83, 0x4000
	s_nop 0
	global_load_lds_dwordx4 v199, s[70:71]
	s_add_i32 m0, s83, 0x6000
	s_nop 0
	global_load_lds_dwordx4 v200, s[70:71]
	s_mov_b32 m0, s60
	s_nop 0
	global_load_lds_dwordx4 v199, s[72:73]
	s_add_i32 m0, s60, 0x2000
	s_nop 0
	global_load_lds_dwordx4 v200, s[72:73]
	ds_read_b128 v[130:133], v216 offset:0
	ds_read_b128 v[134:137], v216 offset:2048
	ds_read_b128 v[138:141], v216 offset:4096
	ds_read_b128 v[142:145], v216 offset:6144
	ds_read_b128 v[162:165], v219 offset:0
	ds_read_b128 v[166:169], v219 offset:2048
	ds_read_b128 v[170:173], v219 offset:4096
	ds_read_b128 v[174:177], v219 offset:6144
	ds_read_b128 v[146:149], v216 offset:1024
	ds_read_b128 v[150:153], v216 offset:3072
	ds_read_b128 v[154:157], v216 offset:5120
	ds_read_b128 v[158:161], v216 offset:7168
	ds_read_b128 v[178:181], v219 offset:1024
	ds_read_b128 v[182:185], v219 offset:3072
	ds_read_b128 v[186:189], v219 offset:5120
	ds_read_b128 v[190:193], v219 offset:7168
	s_waitcnt lgkmcnt(8)
	v_mfma_f32_16x16x32_bf16 v[2:5], v[162:165], v[130:133], v[2:5]
	v_mfma_f32_16x16x32_bf16 v[6:9], v[166:169], v[130:133], v[6:9]
	v_mfma_f32_16x16x32_bf16 v[10:13], v[170:173], v[130:133], v[10:13]
	v_mfma_f32_16x16x32_bf16 v[14:17], v[174:177], v[130:133], v[14:17]
	v_mfma_f32_16x16x32_bf16 v[18:21], v[162:165], v[134:137], v[18:21]
	v_mfma_f32_16x16x32_bf16 v[22:25], v[166:169], v[134:137], v[22:25]
	v_mfma_f32_16x16x32_bf16 v[26:29], v[170:173], v[134:137], v[26:29]
	v_mfma_f32_16x16x32_bf16 v[30:33], v[174:177], v[134:137], v[30:33]
	v_mfma_f32_16x16x32_bf16 v[34:37], v[162:165], v[138:141], v[34:37]
	v_mfma_f32_16x16x32_bf16 v[38:41], v[166:169], v[138:141], v[38:41]
	v_mfma_f32_16x16x32_bf16 v[42:45], v[170:173], v[138:141], v[42:45]
	v_mfma_f32_16x16x32_bf16 v[46:49], v[174:177], v[138:141], v[46:49]
	v_mfma_f32_16x16x32_bf16 v[50:53], v[162:165], v[142:145], v[50:53]
	v_mfma_f32_16x16x32_bf16 v[54:57], v[166:169], v[142:145], v[54:57]
	v_mfma_f32_16x16x32_bf16 v[58:61], v[170:173], v[142:145], v[58:61]
	v_mfma_f32_16x16x32_bf16 v[62:65], v[174:177], v[142:145], v[62:65]
	s_waitcnt lgkmcnt(0)
; __device__ __forceinline__ unsigned cvtpk(float lo, float hi) { f32x2 v = {lo, hi}; bf16x2_t b = __builtin_convertvector(v, bf16x2_t); return __builtin_bit_cast(unsigned, b); }
; __device__ __forceinline__ void branch_phase(LAS unsigned char* lds, const bf16_t* __restrict__ O, const bf16_t* __restrict__ Wb, const bf16_t* __restrict__ Gt, bf16_t* __restrict__ MG, int tg, int wv) {
;     ...
; #pragma unroll
;                     for (int m = 0; m < 4; ++m)
; #pragma unroll
;                         for (int n = 0; n < 4; ++n) acc[m][n] = __builtin_amdgcn_mfma_f32_16x16x32_bf16(bfr[n], af[m], acc[m][n], 0, 0, 0);
;                 }
;                 asm volatile("s_waitcnt vmcnt(0)" ::: "memory"); __syncthreads();
;             }
; #pragma unroll
;             for (int m = 0; m < 4; ++m)
; #pragma unroll
;                 for (int n = 0; n < 4; ++n) { const u32x2 g = gv[m][n], sp = sum[m][n];
;                     const float s0_ = __builtin_bit_cast(float, sp.x << 16) + acc[m][n][0] * __builtin_bit_cast(float, g.x << 16), s1_ = __builtin_bit_cast(float, sp.x & 0xffff0000u) + acc[m][n][1] * __builtin_bit_cast(float, g.x & 0xffff0000u);
;                     const float s2_ = __builtin_bit_cast(float, sp.y << 16) + acc[m][n][2] * __builtin_bit_cast(float, g.y << 16), s3_ = __builtin_bit_cast(float, sp.y & 0xffff0000u) + acc[m][n][3] * __builtin_bit_cast(float, g.y & 0xffff0000u);
;                     sum[m][n] = (u32x2){cvtpk(s0_, s1_), cvtpk(s2_, s3_)}; }
	v_mfma_f32_16x16x32_bf16 v[2:5], v[178:181], v[146:149], v[2:5]
	v_mfma_f32_16x16x32_bf16 v[6:9], v[182:185], v[146:149], v[6:9]
	v_mfma_f32_16x16x32_bf16 v[10:13], v[186:189], v[146:149], v[10:13]
	v_mfma_f32_16x16x32_bf16 v[14:17], v[190:193], v[146:149], v[14:17]
	v_mfma_f32_16x16x32_bf16 v[18:21], v[178:181], v[150:153], v[18:21]
	v_mfma_f32_16x16x32_bf16 v[22:25], v[182:185], v[150:153], v[22:25]
	v_mfma_f32_16x16x32_bf16 v[26:29], v[186:189], v[150:153], v[26:29]
	v_mfma_f32_16x16x32_bf16 v[30:33], v[190:193], v[150:153], v[30:33]
	v_mfma_f32_16x16x32_bf16 v[34:37], v[178:181], v[154:157], v[34:37]
	v_mfma_f32_16x16x32_bf16 v[38:41], v[182:185], v[154:157], v[38:41]
	v_mfma_f32_16x16x32_bf16 v[42:45], v[186:189], v[154:157], v[42:45]
	v_mfma_f32_16x16x32_bf16 v[46:49], v[190:193], v[154:157], v[46:49]
	v_mfma_f32_16x16x32_bf16 v[50:53], v[178:181], v[158:161], v[50:53]
	v_mfma_f32_16x16x32_bf16 v[54:57], v[182:185], v[158:161], v[54:57]
	v_mfma_f32_16x16x32_bf16 v[58:61], v[186:189], v[158:161], v[58:61]
	v_mfma_f32_16x16x32_bf16 v[62:65], v[190:193], v[158:161], v[62:65]
	s_waitcnt vmcnt(6)
	s_barrier
	s_nop 7
	v_lshlrev_b32_e32 v206, 16, v98
	v_and_b32_e32 v207, 0xffff0000, v98
	v_lshlrev_b32_e32 v208, 16, v99
	v_and_b32_e32 v209, 0xffff0000, v99
	v_lshlrev_b32_e32 v210, 16, v66
	v_and_b32_e32 v211, 0xffff0000, v66
	v_lshlrev_b32_e32 v212, 16, v67
	v_and_b32_e32 v213, 0xffff0000, v67
	v_pk_fma_f32 v[210:211], v[2:3], v[206:207], v[210:211]
	v_pk_fma_f32 v[212:213], v[4:5], v[208:209], v[212:213]
	v_cvt_pk_bf16_f32 v66, v210, v211
	v_cvt_pk_bf16_f32 v67, v212, v213
	v_lshlrev_b32_e32 v206, 16, v100
	v_and_b32_e32 v207, 0xffff0000, v100
	v_lshlrev_b32_e32 v208, 16, v101
	v_and_b32_e32 v209, 0xffff0000, v101
	v_lshlrev_b32_e32 v210, 16, v68
	v_and_b32_e32 v211, 0xffff0000, v68
	v_lshlrev_b32_e32 v212, 16, v69
	v_and_b32_e32 v213, 0xffff0000, v69
	v_pk_fma_f32 v[210:211], v[6:7], v[206:207], v[210:211]
	v_pk_fma_f32 v[212:213], v[8:9], v[208:209], v[212:213]
	v_cvt_pk_bf16_f32 v68, v210, v211
	v_cvt_pk_bf16_f32 v69, v212, v213
	v_lshlrev_b32_e32 v206, 16, v102
	v_and_b32_e32 v207, 0xffff0000, v102
	v_lshlrev_b32_e32 v208, 16, v103
	v_and_b32_e32 v209, 0xffff0000, v103
	v_lshlrev_b32_e32 v210, 16, v70
	v_and_b32_e32 v211, 0xffff0000, v70
	v_lshlrev_b32_e32 v212, 16, v71
	v_and_b32_e32 v213, 0xffff0000, v71
	v_pk_fma_f32 v[210:211], v[10:11], v[206:207], v[210:211]
	v_pk_fma_f32 v[212:213], v[12:13], v[208:209], v[212:213]
	v_cvt_pk_bf16_f32 v70, v210, v211
	v_cvt_pk_bf16_f32 v71, v212, v213
	v_lshlrev_b32_e32 v206, 16, v104
	v_and_b32_e32 v207, 0xffff0000, v104
	v_lshlrev_b32_e32 v208, 16, v105
	v_and_b32_e32 v209, 0xffff0000, v105
	v_lshlrev_b32_e32 v210, 16, v72
	v_and_b32_e32 v211, 0xffff0000, v72
	v_lshlrev_b32_e32 v212, 16, v73
	v_and_b32_e32 v213, 0xffff0000, v73
	v_pk_fma_f32 v[210:211], v[14:15], v[206:207], v[210:211]
	v_pk_fma_f32 v[212:213], v[16:17], v[208:209], v[212:213]
	v_cvt_pk_bf16_f32 v72, v210, v211
	v_cvt_pk_bf16_f32 v73, v212, v213
	v_lshlrev_b32_e32 v206, 16, v106
	v_and_b32_e32 v207, 0xffff0000, v106
	v_lshlrev_b32_e32 v208, 16, v107
	v_and_b32_e32 v209, 0xffff0000, v107
	v_lshlrev_b32_e32 v210, 16, v74
	v_and_b32_e32 v211, 0xffff0000, v74
	v_lshlrev_b32_e32 v212, 16, v75
	v_and_b32_e32 v213, 0xffff0000, v75
	v_pk_fma_f32 v[210:211], v[18:19], v[206:207], v[210:211]
	v_pk_fma_f32 v[212:213], v[20:21], v[208:209], v[212:213]
	v_cvt_pk_bf16_f32 v74, v210, v211
	v_cvt_pk_bf16_f32 v75, v212, v213
	v_lshlrev_b32_e32 v206, 16, v108
	v_and_b32_e32 v207, 0xffff0000, v108
	v_lshlrev_b32_e32 v208, 16, v109
	v_and_b32_e32 v209, 0xffff0000, v109
	v_lshlrev_b32_e32 v210, 16, v76
	v_and_b32_e32 v211, 0xffff0000, v76
	v_lshlrev_b32_e32 v212, 16, v77
	v_and_b32_e32 v213, 0xffff0000, v77
	v_pk_fma_f32 v[210:211], v[22:23], v[206:207], v[210:211]
	v_pk_fma_f32 v[212:213], v[24:25], v[208:209], v[212:213]
	v_cvt_pk_bf16_f32 v76, v210, v211
	v_cvt_pk_bf16_f32 v77, v212, v213
	v_lshlrev_b32_e32 v206, 16, v110
	v_and_b32_e32 v207, 0xffff0000, v110
	v_lshlrev_b32_e32 v208, 16, v111
	v_and_b32_e32 v209, 0xffff0000, v111
	v_lshlrev_b32_e32 v210, 16, v78
	v_and_b32_e32 v211, 0xffff0000, v78
	v_lshlrev_b32_e32 v212, 16, v79
	v_and_b32_e32 v213, 0xffff0000, v79
	v_pk_fma_f32 v[210:211], v[26:27], v[206:207], v[210:211]
	v_pk_fma_f32 v[212:213], v[28:29], v[208:209], v[212:213]
	v_cvt_pk_bf16_f32 v78, v210, v211
	v_cvt_pk_bf16_f32 v79, v212, v213
	v_lshlrev_b32_e32 v206, 16, v112
	v_and_b32_e32 v207, 0xffff0000, v112
	v_lshlrev_b32_e32 v208, 16, v113
	v_and_b32_e32 v209, 0xffff0000, v113
	v_lshlrev_b32_e32 v210, 16, v80
	v_and_b32_e32 v211, 0xffff0000, v80
	v_lshlrev_b32_e32 v212, 16, v81
	v_and_b32_e32 v213, 0xffff0000, v81
	v_pk_fma_f32 v[210:211], v[30:31], v[206:207], v[210:211]
	v_pk_fma_f32 v[212:213], v[32:33], v[208:209], v[212:213]
	v_cvt_pk_bf16_f32 v80, v210, v211
	v_cvt_pk_bf16_f32 v81, v212, v213
	v_lshlrev_b32_e32 v206, 16, v114
	v_and_b32_e32 v207, 0xffff0000, v114
	v_lshlrev_b32_e32 v208, 16, v115
	v_and_b32_e32 v209, 0xffff0000, v115
	v_lshlrev_b32_e32 v210, 16, v82
	v_and_b32_e32 v211, 0xffff0000, v82
	v_lshlrev_b32_e32 v212, 16, v83
	v_and_b32_e32 v213, 0xffff0000, v83
	v_pk_fma_f32 v[210:211], v[34:35], v[206:207], v[210:211]
	v_pk_fma_f32 v[212:213], v[36:37], v[208:209], v[212:213]
	v_cvt_pk_bf16_f32 v82, v210, v211
	v_cvt_pk_bf16_f32 v83, v212, v213
	v_lshlrev_b32_e32 v206, 16, v116
	v_and_b32_e32 v207, 0xffff0000, v116
	v_lshlrev_b32_e32 v208, 16, v117
	v_and_b32_e32 v209, 0xffff0000, v117
	v_lshlrev_b32_e32 v210, 16, v84
	v_and_b32_e32 v211, 0xffff0000, v84
	v_lshlrev_b32_e32 v212, 16, v85
	v_and_b32_e32 v213, 0xffff0000, v85
; __device__ __forceinline__ void branch_phase(LAS unsigned char* lds, const bf16_t* __restrict__ O, const bf16_t* __restrict__ Wb, const bf16_t* __restrict__ Gt, bf16_t* __restrict__ MG, int tg, int wv) {
;     ...
;         BR_LOAD(0, 0);
;         asm volatile("s_waitcnt vmcnt(0)" ::: "memory"); __syncthreads();
;         for (int j = 0; j < 4; ++j) {
;             u32x2 gv[4][4];
;             f32x4 acc[4][4];
; #pragma unroll
;             for (int m = 0; m < 4; ++m)
; #pragma unroll
;                 for (int n = 0; n < 4; ++n) acc[m][n] = (f32x4){0.f, 0.f, 0.f, 0.f};
;             for (int kc = 0; kc < 4; ++kc) {
;                 const int c = j * 4 + kc;
;                 if (c + 1 < 16) BR_LOAD(c + 1, (c + 1) & 1);
;                 if (kc == 3) {
;                     const bf16_t* gp = Gt + (size_t)(rt * 128 + wm * 64 + fr) * ZC + j * 1024 + ct * 256 + wn * 64 + 4 * fq;
; #pragma unroll
;                     for (int m = 0; m < 4; ++m)
; #pragma unroll
;                         for (int n = 0; n < 4; ++n) gv[m][n] = *(const u32x2*)(gp + (size_t)m * 16 * ZC + n * 16);
;                 }
;                 LAS const unsigned char* st = lds + (c & 1) * STG;
; #pragma unroll
;                 for (int k = 0; k < 2; ++k) {
;                     __builtin_amdgcn_sched_barrier(0);
;                     bf16x8 af[4], bfr[4];
; #pragma unroll
;                     for (int m = 0; m < 4; ++m) af[m] = *(LAS const bf16x8*)(st + aoff + m * 2048 + k * 1024);
; #pragma unroll
;                     for (int n = 0; n < 4; ++n) bfr[n] = *(LAS const bf16x8*)(st + boff + n * 2048 + k * 1024);
; #pragma unroll
;                     for (int m = 0; m < 4; ++m)
; #pragma unroll
;                         for (int n = 0; n < 4; ++n) acc[m][n] = __builtin_amdgcn_mfma_f32_16x16x32_bf16(bfr[n], af[m], acc[m][n], 0, 0, 0);
;                 }
;                 asm volatile("s_waitcnt vmcnt(0)" ::: "memory"); __syncthreads();
;             }
; #pragma unroll
;             for (int m = 0; m < 4; ++m)
; #pragma unroll
;                 for (int n = 0; n < 4; ++n) { const u32x2 g = gv[m][n], sp = sum[m][n];
;                     const float s0_ = __builtin_bit_cast(float, sp.x << 16) + acc[m][n][0] * __builtin_bit_cast(float, g.x << 16), s1_ = __builtin_bit_cast(float, sp.x & 0xffff0000u) + acc[m][n][1] * __builtin_bit_cast(float, g.x & 0xffff0000u);
	v_pk_fma_f32 v[210:211], v[38:39], v[206:207], v[210:211]
	v_pk_fma_f32 v[212:213], v[40:41], v[208:209], v[212:213]
	v_cvt_pk_bf16_f32 v84, v210, v211
	v_cvt_pk_bf16_f32 v85, v212, v213
	v_lshlrev_b32_e32 v206, 16, v118
	v_and_b32_e32 v207, 0xffff0000, v118
	v_lshlrev_b32_e32 v208, 16, v119
	v_and_b32_e32 v209, 0xffff0000, v119
	v_lshlrev_b32_e32 v210, 16, v86
	v_and_b32_e32 v211, 0xffff0000, v86
	v_lshlrev_b32_e32 v212, 16, v87
	v_and_b32_e32 v213, 0xffff0000, v87
	v_pk_fma_f32 v[210:211], v[42:43], v[206:207], v[210:211]
	v_pk_fma_f32 v[212:213], v[44:45], v[208:209], v[212:213]
	v_cvt_pk_bf16_f32 v86, v210, v211
	v_cvt_pk_bf16_f32 v87, v212, v213
	v_lshlrev_b32_e32 v206, 16, v120
	v_and_b32_e32 v207, 0xffff0000, v120
	v_lshlrev_b32_e32 v208, 16, v121
	v_and_b32_e32 v209, 0xffff0000, v121
	v_lshlrev_b32_e32 v210, 16, v88
	v_and_b32_e32 v211, 0xffff0000, v88
	v_lshlrev_b32_e32 v212, 16, v89
	v_and_b32_e32 v213, 0xffff0000, v89
	v_pk_fma_f32 v[210:211], v[46:47], v[206:207], v[210:211]
	v_pk_fma_f32 v[212:213], v[48:49], v[208:209], v[212:213]
	v_cvt_pk_bf16_f32 v88, v210, v211
	v_cvt_pk_bf16_f32 v89, v212, v213
	v_lshlrev_b32_e32 v206, 16, v122
	v_and_b32_e32 v207, 0xffff0000, v122
	v_lshlrev_b32_e32 v208, 16, v123
	v_and_b32_e32 v209, 0xffff0000, v123
	v_lshlrev_b32_e32 v210, 16, v90
	v_and_b32_e32 v211, 0xffff0000, v90
	v_lshlrev_b32_e32 v212, 16, v91
	v_and_b32_e32 v213, 0xffff0000, v91
	v_pk_fma_f32 v[210:211], v[50:51], v[206:207], v[210:211]
	v_pk_fma_f32 v[212:213], v[52:53], v[208:209], v[212:213]
	v_cvt_pk_bf16_f32 v90, v210, v211
	v_cvt_pk_bf16_f32 v91, v212, v213
	v_lshlrev_b32_e32 v206, 16, v124
	v_and_b32_e32 v207, 0xffff0000, v124
	v_lshlrev_b32_e32 v208, 16, v125
	v_and_b32_e32 v209, 0xffff0000, v125
	v_lshlrev_b32_e32 v210, 16, v92
	v_and_b32_e32 v211, 0xffff0000, v92
	v_lshlrev_b32_e32 v212, 16, v93
	v_and_b32_e32 v213, 0xffff0000, v93
	v_pk_fma_f32 v[210:211], v[54:55], v[206:207], v[210:211]
	v_pk_fma_f32 v[212:213], v[56:57], v[208:209], v[212:213]
	v_cvt_pk_bf16_f32 v92, v210, v211
	v_cvt_pk_bf16_f32 v93, v212, v213
	v_lshlrev_b32_e32 v206, 16, v126
	v_and_b32_e32 v207, 0xffff0000, v126
	v_lshlrev_b32_e32 v208, 16, v127
	v_and_b32_e32 v209, 0xffff0000, v127
	v_lshlrev_b32_e32 v210, 16, v94
	v_and_b32_e32 v211, 0xffff0000, v94
	v_lshlrev_b32_e32 v212, 16, v95
	v_and_b32_e32 v213, 0xffff0000, v95
	v_pk_fma_f32 v[210:211], v[58:59], v[206:207], v[210:211]
	v_pk_fma_f32 v[212:213], v[60:61], v[208:209], v[212:213]
	v_cvt_pk_bf16_f32 v94, v210, v211
	v_cvt_pk_bf16_f32 v95, v212, v213
	v_lshlrev_b32_e32 v206, 16, v128
	v_and_b32_e32 v207, 0xffff0000, v128
	v_lshlrev_b32_e32 v208, 16, v129
	v_and_b32_e32 v209, 0xffff0000, v129
	v_lshlrev_b32_e32 v210, 16, v96
	v_and_b32_e32 v211, 0xffff0000, v96
	v_lshlrev_b32_e32 v212, 16, v97
	v_and_b32_e32 v213, 0xffff0000, v97
	v_pk_fma_f32 v[210:211], v[62:63], v[206:207], v[210:211]
	v_pk_fma_f32 v[212:213], v[64:65], v[208:209], v[212:213]
	v_cvt_pk_bf16_f32 v96, v210, v211
	v_cvt_pk_bf16_f32 v97, v212, v213
	s_add_u32 s66, s64, 0x700
	s_addc_u32 s67, s65, 0
	s_add_u32 s70, s68, 0x180100
	s_addc_u32 s71, s69, 0
	s_add_u32 s72, s70, 0x10000
	s_addc_u32 s73, s71, 0
	s_mov_b32 m0, s84
	s_nop 0
	global_load_lds_dwordx4 v197, s[66:67]
	s_add_i32 m0, s84, 0x2000
	s_nop 0
	global_load_lds_dwordx4 v198, s[66:67]
	s_add_i32 m0, s84, 0x4000
	s_nop 0
	global_load_lds_dwordx4 v199, s[70:71]
	s_add_i32 m0, s84, 0x6000
	s_nop 0
	global_load_lds_dwordx4 v200, s[70:71]
	s_mov_b32 m0, s61
	s_nop 0
	global_load_lds_dwordx4 v199, s[72:73]
	s_add_i32 m0, s61, 0x2000
	s_nop 0
	global_load_lds_dwordx4 v200, s[72:73]
	ds_read_b128 v[130:133], v214 offset:0
	ds_read_b128 v[134:137], v214 offset:2048
	ds_read_b128 v[138:141], v214 offset:4096
	ds_read_b128 v[142:145], v214 offset:6144
	ds_read_b128 v[162:165], v217 offset:0
	ds_read_b128 v[166:169], v217 offset:2048
	ds_read_b128 v[170:173], v217 offset:4096
	ds_read_b128 v[174:177], v217 offset:6144
	ds_read_b128 v[146:149], v214 offset:1024
	ds_read_b128 v[150:153], v214 offset:3072
	ds_read_b128 v[154:157], v214 offset:5120
	ds_read_b128 v[158:161], v214 offset:7168
	ds_read_b128 v[178:181], v217 offset:1024
	ds_read_b128 v[182:185], v217 offset:3072
	ds_read_b128 v[186:189], v217 offset:5120
	ds_read_b128 v[190:193], v217 offset:7168
	s_waitcnt lgkmcnt(8)
	v_mfma_f32_16x16x32_bf16 v[2:5], v[162:165], v[130:133], 0
	v_mfma_f32_16x16x32_bf16 v[6:9], v[166:169], v[130:133], 0
	v_mfma_f32_16x16x32_bf16 v[10:13], v[170:173], v[130:133], 0
	v_mfma_f32_16x16x32_bf16 v[14:17], v[174:177], v[130:133], 0
	v_mfma_f32_16x16x32_bf16 v[18:21], v[162:165], v[134:137], 0
	v_mfma_f32_16x16x32_bf16 v[22:25], v[166:169], v[134:137], 0
	v_mfma_f32_16x16x32_bf16 v[26:29], v[170:173], v[134:137], 0
	v_mfma_f32_16x16x32_bf16 v[30:33], v[174:177], v[134:137], 0
	v_mfma_f32_16x16x32_bf16 v[34:37], v[162:165], v[138:141], 0
	v_mfma_f32_16x16x32_bf16 v[38:41], v[166:169], v[138:141], 0
	v_mfma_f32_16x16x32_bf16 v[42:45], v[170:173], v[138:141], 0
	v_mfma_f32_16x16x32_bf16 v[46:49], v[174:177], v[138:141], 0
	v_mfma_f32_16x16x32_bf16 v[50:53], v[162:165], v[142:145], 0
	v_mfma_f32_16x16x32_bf16 v[54:57], v[166:169], v[142:145], 0
	v_mfma_f32_16x16x32_bf16 v[58:61], v[170:173], v[142:145], 0
	v_mfma_f32_16x16x32_bf16 v[62:65], v[174:177], v[142:145], 0
	s_waitcnt lgkmcnt(0)
	v_mfma_f32_16x16x32_bf16 v[2:5], v[178:181], v[146:149], v[2:5]
	v_mfma_f32_16x16x32_bf16 v[6:9], v[182:185], v[146:149], v[6:9]
	v_mfma_f32_16x16x32_bf16 v[10:13], v[186:189], v[146:149], v[10:13]
	v_mfma_f32_16x16x32_bf16 v[14:17], v[190:193], v[146:149], v[14:17]
	v_mfma_f32_16x16x32_bf16 v[18:21], v[178:181], v[150:153], v[18:21]
	v_mfma_f32_16x16x32_bf16 v[22:25], v[182:185], v[150:153], v[22:25]
	v_mfma_f32_16x16x32_bf16 v[26:29], v[186:189], v[150:153], v[26:29]
	v_mfma_f32_16x16x32_bf16 v[30:33], v[190:193], v[150:153], v[30:33]
	v_mfma_f32_16x16x32_bf16 v[34:37], v[178:181], v[154:157], v[34:37]
	v_mfma_f32_16x16x32_bf16 v[38:41], v[182:185], v[154:157], v[38:41]
	v_mfma_f32_16x16x32_bf16 v[42:45], v[186:189], v[154:157], v[42:45]
	v_mfma_f32_16x16x32_bf16 v[46:49], v[190:193], v[154:157], v[46:49]
	v_mfma_f32_16x16x32_bf16 v[50:53], v[178:181], v[158:161], v[50:53]
	v_mfma_f32_16x16x32_bf16 v[54:57], v[182:185], v[158:161], v[54:57]
	v_mfma_f32_16x16x32_bf16 v[58:61], v[186:189], v[158:161], v[58:61]
	v_mfma_f32_16x16x32_bf16 v[62:65], v[190:193], v[158:161], v[62:65]
	s_waitcnt vmcnt(6)
	s_barrier
; #define LAS __attribute__((address_space(3)))
; __device__ __forceinline__ void branch_phase(LAS unsigned char* lds, const bf16_t* __restrict__ O, const bf16_t* __restrict__ Wb, const bf16_t* __restrict__ Gt, bf16_t* __restrict__ MG, int tg, int wv) {
;     ...
;             for (int kc = 0; kc < 4; ++kc) {
;                 const int c = j * 4 + kc;
;                 if (c + 1 < 16) BR_LOAD(c + 1, (c + 1) & 1);
;                 if (kc == 3) {
;                     const bf16_t* gp = Gt + (size_t)(rt * 128 + wm * 64 + fr) * ZC + j * 1024 + ct * 256 + wn * 64 + 4 * fq;
; #pragma unroll
;                     for (int m = 0; m < 4; ++m)
; #pragma unroll
;                         for (int n = 0; n < 4; ++n) gv[m][n] = *(const u32x2*)(gp + (size_t)m * 16 * ZC + n * 16);
;                 }
;                 LAS const unsigned char* st = lds + (c & 1) * STG;
; #pragma unroll
;                 for (int k = 0; k < 2; ++k) {
;                     __builtin_amdgcn_sched_barrier(0);
;                     bf16x8 af[4], bfr[4];
; #pragma unroll
;                     for (int m = 0; m < 4; ++m) af[m] = *(LAS const bf16x8*)(st + aoff + m * 2048 + k * 1024);
; #pragma unroll
;                     for (int n = 0; n < 4; ++n) bfr[n] = *(LAS const bf16x8*)(st + boff + n * 2048 + k * 1024);
; #pragma unroll
;                     for (int m = 0; m < 4; ++m)
; #pragma unroll
;                         for (int n = 0; n < 4; ++n) acc[m][n] = __builtin_amdgcn_mfma_f32_16x16x32_bf16(bfr[n], af[m], acc[m][n], 0, 0, 0);
;                 }
;                 asm volatile("s_waitcnt vmcnt(0)" ::: "memory"); __syncthreads();
	s_add_u32 s66, s64, 0x780
	s_addc_u32 s67, s65, 0
	s_add_u32 s70, s68, 0x180180
	s_addc_u32 s71, s69, 0
	s_add_u32 s72, s70, 0x10000
	s_addc_u32 s73, s71, 0
	s_mov_b32 m0, s82
	s_nop 0
	global_load_lds_dwordx4 v197, s[66:67]
	s_add_i32 m0, s82, 0x2000
	s_nop 0
	global_load_lds_dwordx4 v198, s[66:67]
	s_add_i32 m0, s82, 0x4000
	s_nop 0
	global_load_lds_dwordx4 v199, s[70:71]
	s_add_i32 m0, s82, 0x6000
	s_nop 0
	global_load_lds_dwordx4 v200, s[70:71]
	s_mov_b32 m0, s85
	s_nop 0
	global_load_lds_dwordx4 v199, s[72:73]
	s_add_i32 m0, s85, 0x2000
	s_nop 0
	global_load_lds_dwordx4 v200, s[72:73]
	s_add_u32 s80, s74, 0x1800
	s_addc_u32 s81, s75, 0
	global_load_dwordx2 v[98:99], v204, s[80:81] offset:0
	global_load_dwordx2 v[100:101], v204, s[80:81] offset:32
	global_load_dwordx2 v[102:103], v204, s[80:81] offset:64
	global_load_dwordx2 v[104:105], v204, s[80:81] offset:96
	s_add_u32 s80, s80, 0x20000
	s_addc_u32 s81, s81, 0
	global_load_dwordx2 v[106:107], v204, s[80:81] offset:0
	global_load_dwordx2 v[108:109], v204, s[80:81] offset:32
	global_load_dwordx2 v[110:111], v204, s[80:81] offset:64
	global_load_dwordx2 v[112:113], v204, s[80:81] offset:96
	s_add_u32 s80, s80, 0x20000
	s_addc_u32 s81, s81, 0
	global_load_dwordx2 v[114:115], v204, s[80:81] offset:0
	global_load_dwordx2 v[116:117], v204, s[80:81] offset:32
	global_load_dwordx2 v[118:119], v204, s[80:81] offset:64
	global_load_dwordx2 v[120:121], v204, s[80:81] offset:96
	s_add_u32 s80, s80, 0x20000
	s_addc_u32 s81, s81, 0
	global_load_dwordx2 v[122:123], v204, s[80:81] offset:0
	global_load_dwordx2 v[124:125], v204, s[80:81] offset:32
	global_load_dwordx2 v[126:127], v204, s[80:81] offset:64
	global_load_dwordx2 v[128:129], v204, s[80:81] offset:96
	ds_read_b128 v[130:133], v215 offset:0
	ds_read_b128 v[134:137], v215 offset:2048
	ds_read_b128 v[138:141], v215 offset:4096
	ds_read_b128 v[142:145], v215 offset:6144
	ds_read_b128 v[162:165], v218 offset:0
	ds_read_b128 v[166:169], v218 offset:2048
	ds_read_b128 v[170:173], v218 offset:4096
	ds_read_b128 v[174:177], v218 offset:6144
	ds_read_b128 v[146:149], v215 offset:1024
	ds_read_b128 v[150:153], v215 offset:3072
	ds_read_b128 v[154:157], v215 offset:5120
	ds_read_b128 v[158:161], v215 offset:7168
	ds_read_b128 v[178:181], v218 offset:1024
	ds_read_b128 v[182:185], v218 offset:3072
	ds_read_b128 v[186:189], v218 offset:5120
	ds_read_b128 v[190:193], v218 offset:7168
	s_waitcnt lgkmcnt(8)
	v_mfma_f32_16x16x32_bf16 v[2:5], v[162:165], v[130:133], v[2:5]
	v_mfma_f32_16x16x32_bf16 v[6:9], v[166:169], v[130:133], v[6:9]
	v_mfma_f32_16x16x32_bf16 v[10:13], v[170:173], v[130:133], v[10:13]
	v_mfma_f32_16x16x32_bf16 v[14:17], v[174:177], v[130:133], v[14:17]
	v_mfma_f32_16x16x32_bf16 v[18:21], v[162:165], v[134:137], v[18:21]
	v_mfma_f32_16x16x32_bf16 v[22:25], v[166:169], v[134:137], v[22:25]
	v_mfma_f32_16x16x32_bf16 v[26:29], v[170:173], v[134:137], v[26:29]
	v_mfma_f32_16x16x32_bf16 v[30:33], v[174:177], v[134:137], v[30:33]
	v_mfma_f32_16x16x32_bf16 v[34:37], v[162:165], v[138:141], v[34:37]
	v_mfma_f32_16x16x32_bf16 v[38:41], v[166:169], v[138:141], v[38:41]
	v_mfma_f32_16x16x32_bf16 v[42:45], v[170:173], v[138:141], v[42:45]
	v_mfma_f32_16x16x32_bf16 v[46:49], v[174:177], v[138:141], v[46:49]
	v_mfma_f32_16x16x32_bf16 v[50:53], v[162:165], v[142:145], v[50:53]
	v_mfma_f32_16x16x32_bf16 v[54:57], v[166:169], v[142:145], v[54:57]
	v_mfma_f32_16x16x32_bf16 v[58:61], v[170:173], v[142:145], v[58:61]
	v_mfma_f32_16x16x32_bf16 v[62:65], v[174:177], v[142:145], v[62:65]
	s_waitcnt lgkmcnt(0)
	v_mfma_f32_16x16x32_bf16 v[2:5], v[178:181], v[146:149], v[2:5]
	v_mfma_f32_16x16x32_bf16 v[6:9], v[182:185], v[146:149], v[6:9]
	v_mfma_f32_16x16x32_bf16 v[10:13], v[186:189], v[146:149], v[10:13]
	v_mfma_f32_16x16x32_bf16 v[14:17], v[190:193], v[146:149], v[14:17]
	v_mfma_f32_16x16x32_bf16 v[18:21], v[178:181], v[150:153], v[18:21]
	v_mfma_f32_16x16x32_bf16 v[22:25], v[182:185], v[150:153], v[22:25]
	v_mfma_f32_16x16x32_bf16 v[26:29], v[186:189], v[150:153], v[26:29]
	v_mfma_f32_16x16x32_bf16 v[30:33], v[190:193], v[150:153], v[30:33]
	v_mfma_f32_16x16x32_bf16 v[34:37], v[178:181], v[154:157], v[34:37]
	v_mfma_f32_16x16x32_bf16 v[38:41], v[182:185], v[154:157], v[38:41]
	v_mfma_f32_16x16x32_bf16 v[42:45], v[186:189], v[154:157], v[42:45]
	v_mfma_f32_16x16x32_bf16 v[46:49], v[190:193], v[154:157], v[46:49]
	v_mfma_f32_16x16x32_bf16 v[50:53], v[178:181], v[158:161], v[50:53]
	v_mfma_f32_16x16x32_bf16 v[54:57], v[182:185], v[158:161], v[54:57]
	v_mfma_f32_16x16x32_bf16 v[58:61], v[186:189], v[158:161], v[58:61]
	v_mfma_f32_16x16x32_bf16 v[62:65], v[190:193], v[158:161], v[62:65]
	s_waitcnt vmcnt(22)
	s_barrier
; #define LAS __attribute__((address_space(3)))
; __device__ __forceinline__ void branch_phase(LAS unsigned char* lds, const bf16_t* __restrict__ O, const bf16_t* __restrict__ Wb, const bf16_t* __restrict__ Gt, bf16_t* __restrict__ MG, int tg, int wv) {
;     ...
;         BR_LOAD(0, 0);
;         asm volatile("s_waitcnt vmcnt(0)" ::: "memory"); __syncthreads();
;         for (int j = 0; j < 4; ++j) {
;             u32x2 gv[4][4];
;             f32x4 acc[4][4];
; #pragma unroll
;             for (int m = 0; m < 4; ++m)
; #pragma unroll
;                 for (int n = 0; n < 4; ++n) acc[m][n] = (f32x4){0.f, 0.f, 0.f, 0.f};
;             for (int kc = 0; kc < 4; ++kc) {
;                 const int c = j * 4 + kc;
;                 if (c + 1 < 16) BR_LOAD(c + 1, (c + 1) & 1);
;                 if (kc == 3) {
;                     const bf16_t* gp = Gt + (size_t)(rt * 128 + wm * 64 + fr) * ZC + j * 1024 + ct * 256 + wn * 64 + 4 * fq;
; #pragma unroll
;                     for (int m = 0; m < 4; ++m)
; #pragma unroll
;                         for (int n = 0; n < 4; ++n) gv[m][n] = *(const u32x2*)(gp + (size_t)m * 16 * ZC + n * 16);
;                 }
;                 LAS const unsigned char* st = lds + (c & 1) * STG;
; #pragma unroll
;                 for (int k = 0; k < 2; ++k) {
;                     __builtin_amdgcn_sched_barrier(0);
;                     bf16x8 af[4], bfr[4];
; #pragma unroll
;                     for (int m = 0; m < 4; ++m) af[m] = *(LAS const bf16x8*)(st + aoff + m * 2048 + k * 1024);
; #pragma unroll
;                     for (int n = 0; n < 4; ++n) bfr[n] = *(LAS const bf16x8*)(st + boff + n * 2048 + k * 1024);
; #pragma unroll
;                     for (int m = 0; m < 4; ++m)
; #pragma unroll
;                         for (int n = 0; n < 4; ++n) acc[m][n] = __builtin_amdgcn_mfma_f32_16x16x32_bf16(bfr[n], af[m], acc[m][n], 0, 0, 0);
;                 }
;                 asm volatile("s_waitcnt vmcnt(0)" ::: "memory"); __syncthreads();
	ds_read_b128 v[130:133], v216 offset:0
	ds_read_b128 v[134:137], v216 offset:2048
	ds_read_b128 v[138:141], v216 offset:4096
	ds_read_b128 v[142:145], v216 offset:6144
	ds_read_b128 v[162:165], v219 offset:0
	ds_read_b128 v[166:169], v219 offset:2048
	ds_read_b128 v[170:173], v219 offset:4096
	ds_read_b128 v[174:177], v219 offset:6144
	ds_read_b128 v[146:149], v216 offset:1024
	ds_read_b128 v[150:153], v216 offset:3072
	ds_read_b128 v[154:157], v216 offset:5120
	ds_read_b128 v[158:161], v216 offset:7168
	ds_read_b128 v[178:181], v219 offset:1024
	ds_read_b128 v[182:185], v219 offset:3072
	ds_read_b128 v[186:189], v219 offset:5120
	ds_read_b128 v[190:193], v219 offset:7168
	s_waitcnt lgkmcnt(8)
	v_mfma_f32_16x16x32_bf16 v[2:5], v[162:165], v[130:133], v[2:5]
	v_mfma_f32_16x16x32_bf16 v[6:9], v[166:169], v[130:133], v[6:9]
	v_mfma_f32_16x16x32_bf16 v[10:13], v[170:173], v[130:133], v[10:13]
	v_mfma_f32_16x16x32_bf16 v[14:17], v[174:177], v[130:133], v[14:17]
	v_mfma_f32_16x16x32_bf16 v[18:21], v[162:165], v[134:137], v[18:21]
	v_mfma_f32_16x16x32_bf16 v[22:25], v[166:169], v[134:137], v[22:25]
	v_mfma_f32_16x16x32_bf16 v[26:29], v[170:173], v[134:137], v[26:29]
	v_mfma_f32_16x16x32_bf16 v[30:33], v[174:177], v[134:137], v[30:33]
	v_mfma_f32_16x16x32_bf16 v[34:37], v[162:165], v[138:141], v[34:37]
	v_mfma_f32_16x16x32_bf16 v[38:41], v[166:169], v[138:141], v[38:41]
	v_mfma_f32_16x16x32_bf16 v[42:45], v[170:173], v[138:141], v[42:45]
	v_mfma_f32_16x16x32_bf16 v[46:49], v[174:177], v[138:141], v[46:49]
	v_mfma_f32_16x16x32_bf16 v[50:53], v[162:165], v[142:145], v[50:53]
	v_mfma_f32_16x16x32_bf16 v[54:57], v[166:169], v[142:145], v[54:57]
	v_mfma_f32_16x16x32_bf16 v[58:61], v[170:173], v[142:145], v[58:61]
	v_mfma_f32_16x16x32_bf16 v[62:65], v[174:177], v[142:145], v[62:65]
	s_waitcnt lgkmcnt(0)
	v_mfma_f32_16x16x32_bf16 v[2:5], v[178:181], v[146:149], v[2:5]
	v_mfma_f32_16x16x32_bf16 v[6:9], v[182:185], v[146:149], v[6:9]
	v_mfma_f32_16x16x32_bf16 v[10:13], v[186:189], v[146:149], v[10:13]
	v_mfma_f32_16x16x32_bf16 v[14:17], v[190:193], v[146:149], v[14:17]
	v_mfma_f32_16x16x32_bf16 v[18:21], v[178:181], v[150:153], v[18:21]
	v_mfma_f32_16x16x32_bf16 v[22:25], v[182:185], v[150:153], v[22:25]
	v_mfma_f32_16x16x32_bf16 v[26:29], v[186:189], v[150:153], v[26:29]
	v_mfma_f32_16x16x32_bf16 v[30:33], v[190:193], v[150:153], v[30:33]
	v_mfma_f32_16x16x32_bf16 v[34:37], v[178:181], v[154:157], v[34:37]
	v_mfma_f32_16x16x32_bf16 v[38:41], v[182:185], v[154:157], v[38:41]
	v_mfma_f32_16x16x32_bf16 v[42:45], v[186:189], v[154:157], v[42:45]
	v_mfma_f32_16x16x32_bf16 v[46:49], v[190:193], v[154:157], v[46:49]
	v_mfma_f32_16x16x32_bf16 v[50:53], v[178:181], v[158:161], v[50:53]
	v_mfma_f32_16x16x32_bf16 v[54:57], v[182:185], v[158:161], v[54:57]
	v_mfma_f32_16x16x32_bf16 v[58:61], v[186:189], v[158:161], v[58:61]
	v_mfma_f32_16x16x32_bf16 v[62:65], v[190:193], v[158:161], v[62:65]
	s_waitcnt vmcnt(0)
	s_barrier
	s_add_i32 s79, s5, s4
	s_cmp_lt_i32 s79, s6
	s_cbranch_scc0 .Lph6_nopf
	s_add_u32 s64, s64, s62
	s_addc_u32 s65, s65, 0
	s_add_u32 s66, s64, 0x0
	s_addc_u32 s67, s65, 0
	s_add_u32 s70, s68, 0x0
	s_addc_u32 s71, s69, 0
	s_add_u32 s72, s70, 0x10000
	s_addc_u32 s73, s71, 0
	s_mov_b32 m0, s83
	s_nop 0
	global_load_lds_dwordx4 v197, s[66:67]
	s_add_i32 m0, s83, 0x2000
	s_nop 0
	global_load_lds_dwordx4 v198, s[66:67]
	s_add_i32 m0, s83, 0x4000
	s_nop 0
	global_load_lds_dwordx4 v199, s[70:71]
	s_add_i32 m0, s83, 0x6000
	s_nop 0
	global_load_lds_dwordx4 v200, s[70:71]
	s_mov_b32 m0, s60
	s_nop 0
	global_load_lds_dwordx4 v199, s[72:73]
	s_add_i32 m0, s60, 0x2000
	s_nop 0
	global_load_lds_dwordx4 v200, s[72:73]
	s_add_u32 s66, s64, 0x80
	s_addc_u32 s67, s65, 0
	s_add_u32 s70, s68, 0x80
	s_addc_u32 s71, s69, 0
	s_add_u32 s72, s70, 0x10000
	s_addc_u32 s73, s71, 0
	s_mov_b32 m0, s84
	s_nop 0
	global_load_lds_dwordx4 v197, s[66:67]
	s_add_i32 m0, s84, 0x2000
	s_nop 0
	global_load_lds_dwordx4 v198, s[66:67]
	s_add_i32 m0, s84, 0x4000
	s_nop 0
	global_load_lds_dwordx4 v199, s[70:71]
	s_add_i32 m0, s84, 0x6000
	s_nop 0
	global_load_lds_dwordx4 v200, s[70:71]
	s_mov_b32 m0, s61
	s_nop 0
	global_load_lds_dwordx4 v199, s[72:73]
	s_add_i32 m0, s61, 0x2000
	s_nop 0
	global_load_lds_dwordx4 v200, s[72:73]
; #define LAS __attribute__((address_space(3)))
; __device__ __forceinline__ unsigned cvtpk(float lo, float hi) { f32x2 v = {lo, hi}; bf16x2_t b = __builtin_convertvector(v, bf16x2_t); return __builtin_bit_cast(unsigned, b); }
; __device__ __forceinline__ void branch_phase(LAS unsigned char* lds, const bf16_t* __restrict__ O, const bf16_t* __restrict__ Wb, const bf16_t* __restrict__ Gt, bf16_t* __restrict__ MG, int tg, int wv) {
;     ...
;                 LAS const unsigned char* st = lds + (c & 1) * STG;
; #pragma unroll
;                 for (int k = 0; k < 2; ++k) {
;                     __builtin_amdgcn_sched_barrier(0);
;                     bf16x8 af[4], bfr[4];
; #pragma unroll
;                     for (int m = 0; m < 4; ++m) af[m] = *(LAS const bf16x8*)(st + aoff + m * 2048 + k * 1024);
; #pragma unroll
;                     for (int n = 0; n < 4; ++n) bfr[n] = *(LAS const bf16x8*)(st + boff + n * 2048 + k * 1024);
; #pragma unroll
;                     for (int m = 0; m < 4; ++m)
; #pragma unroll
;                         for (int n = 0; n < 4; ++n) acc[m][n] = __builtin_amdgcn_mfma_f32_16x16x32_bf16(bfr[n], af[m], acc[m][n], 0, 0, 0);
;                 }
;                 asm volatile("s_waitcnt vmcnt(0)" ::: "memory"); __syncthreads();
;             }
; #pragma unroll
;             for (int m = 0; m < 4; ++m)
; #pragma unroll
;                 for (int n = 0; n < 4; ++n) { const u32x2 g = gv[m][n], sp = sum[m][n];
;                     const float s0_ = __builtin_bit_cast(float, sp.x << 16) + acc[m][n][0] * __builtin_bit_cast(float, g.x << 16), s1_ = __builtin_bit_cast(float, sp.x & 0xffff0000u) + acc[m][n][1] * __builtin_bit_cast(float, g.x & 0xffff0000u);
;                     const float s2_ = __builtin_bit_cast(float, sp.y << 16) + acc[m][n][2] * __builtin_bit_cast(float, g.y << 16), s3_ = __builtin_bit_cast(float, sp.y & 0xffff0000u) + acc[m][n][3] * __builtin_bit_cast(float, g.y & 0xffff0000u);
;                     sum[m][n] = (u32x2){cvtpk(s0_, s1_), cvtpk(s2_, s3_)}; }
.Lph6_nopf:
	ds_read_b128 v[130:133], v214 offset:0
	ds_read_b128 v[134:137], v214 offset:2048
	ds_read_b128 v[138:141], v214 offset:4096
	ds_read_b128 v[142:145], v214 offset:6144
	ds_read_b128 v[162:165], v217 offset:0
	ds_read_b128 v[166:169], v217 offset:2048
	ds_read_b128 v[170:173], v217 offset:4096
	ds_read_b128 v[174:177], v217 offset:6144
	ds_read_b128 v[146:149], v214 offset:1024
	ds_read_b128 v[150:153], v214 offset:3072
	ds_read_b128 v[154:157], v214 offset:5120
	ds_read_b128 v[158:161], v214 offset:7168
	ds_read_b128 v[178:181], v217 offset:1024
	ds_read_b128 v[182:185], v217 offset:3072
	ds_read_b128 v[186:189], v217 offset:5120
	ds_read_b128 v[190:193], v217 offset:7168
	s_waitcnt lgkmcnt(8)
	v_mfma_f32_16x16x32_bf16 v[2:5], v[162:165], v[130:133], v[2:5]
	v_mfma_f32_16x16x32_bf16 v[6:9], v[166:169], v[130:133], v[6:9]
	v_mfma_f32_16x16x32_bf16 v[10:13], v[170:173], v[130:133], v[10:13]
	v_mfma_f32_16x16x32_bf16 v[14:17], v[174:177], v[130:133], v[14:17]
	v_mfma_f32_16x16x32_bf16 v[18:21], v[162:165], v[134:137], v[18:21]
	v_mfma_f32_16x16x32_bf16 v[22:25], v[166:169], v[134:137], v[22:25]
	v_mfma_f32_16x16x32_bf16 v[26:29], v[170:173], v[134:137], v[26:29]
	v_mfma_f32_16x16x32_bf16 v[30:33], v[174:177], v[134:137], v[30:33]
	v_mfma_f32_16x16x32_bf16 v[34:37], v[162:165], v[138:141], v[34:37]
	v_mfma_f32_16x16x32_bf16 v[38:41], v[166:169], v[138:141], v[38:41]
	v_mfma_f32_16x16x32_bf16 v[42:45], v[170:173], v[138:141], v[42:45]
	v_mfma_f32_16x16x32_bf16 v[46:49], v[174:177], v[138:141], v[46:49]
	v_mfma_f32_16x16x32_bf16 v[50:53], v[162:165], v[142:145], v[50:53]
	v_mfma_f32_16x16x32_bf16 v[54:57], v[166:169], v[142:145], v[54:57]
	v_mfma_f32_16x16x32_bf16 v[58:61], v[170:173], v[142:145], v[58:61]
	v_mfma_f32_16x16x32_bf16 v[62:65], v[174:177], v[142:145], v[62:65]
	s_waitcnt lgkmcnt(0)
	v_mfma_f32_16x16x32_bf16 v[2:5], v[178:181], v[146:149], v[2:5]
	v_mfma_f32_16x16x32_bf16 v[6:9], v[182:185], v[146:149], v[6:9]
	v_mfma_f32_16x16x32_bf16 v[10:13], v[186:189], v[146:149], v[10:13]
	v_mfma_f32_16x16x32_bf16 v[14:17], v[190:193], v[146:149], v[14:17]
	v_mfma_f32_16x16x32_bf16 v[18:21], v[178:181], v[150:153], v[18:21]
	v_mfma_f32_16x16x32_bf16 v[22:25], v[182:185], v[150:153], v[22:25]
	v_mfma_f32_16x16x32_bf16 v[26:29], v[186:189], v[150:153], v[26:29]
	v_mfma_f32_16x16x32_bf16 v[30:33], v[190:193], v[150:153], v[30:33]
	v_mfma_f32_16x16x32_bf16 v[34:37], v[178:181], v[154:157], v[34:37]
	v_mfma_f32_16x16x32_bf16 v[38:41], v[182:185], v[154:157], v[38:41]
	v_mfma_f32_16x16x32_bf16 v[42:45], v[186:189], v[154:157], v[42:45]
	v_mfma_f32_16x16x32_bf16 v[46:49], v[190:193], v[154:157], v[46:49]
	v_mfma_f32_16x16x32_bf16 v[50:53], v[178:181], v[158:161], v[50:53]
	v_mfma_f32_16x16x32_bf16 v[54:57], v[182:185], v[158:161], v[54:57]
	v_mfma_f32_16x16x32_bf16 v[58:61], v[186:189], v[158:161], v[58:61]
	v_mfma_f32_16x16x32_bf16 v[62:65], v[190:193], v[158:161], v[62:65]
	s_nop 7
	v_lshlrev_b32_e32 v206, 16, v98
	v_and_b32_e32 v207, 0xffff0000, v98
	v_lshlrev_b32_e32 v208, 16, v99
	v_and_b32_e32 v209, 0xffff0000, v99
	v_lshlrev_b32_e32 v210, 16, v66
	v_and_b32_e32 v211, 0xffff0000, v66
	v_lshlrev_b32_e32 v212, 16, v67
	v_and_b32_e32 v213, 0xffff0000, v67
	v_pk_fma_f32 v[210:211], v[2:3], v[206:207], v[210:211]
	v_pk_fma_f32 v[212:213], v[4:5], v[208:209], v[212:213]
	v_cvt_pk_bf16_f32 v66, v210, v211
	v_cvt_pk_bf16_f32 v67, v212, v213
	v_lshlrev_b32_e32 v206, 16, v100
	v_and_b32_e32 v207, 0xffff0000, v100
	v_lshlrev_b32_e32 v208, 16, v101
	v_and_b32_e32 v209, 0xffff0000, v101
	v_lshlrev_b32_e32 v210, 16, v68
	v_and_b32_e32 v211, 0xffff0000, v68
	v_lshlrev_b32_e32 v212, 16, v69
	v_and_b32_e32 v213, 0xffff0000, v69
	v_pk_fma_f32 v[210:211], v[6:7], v[206:207], v[210:211]
	v_pk_fma_f32 v[212:213], v[8:9], v[208:209], v[212:213]
	v_cvt_pk_bf16_f32 v68, v210, v211
	v_cvt_pk_bf16_f32 v69, v212, v213
	v_lshlrev_b32_e32 v206, 16, v102
	v_and_b32_e32 v207, 0xffff0000, v102
	v_lshlrev_b32_e32 v208, 16, v103
	v_and_b32_e32 v209, 0xffff0000, v103
	v_lshlrev_b32_e32 v210, 16, v70
	v_and_b32_e32 v211, 0xffff0000, v70
	v_lshlrev_b32_e32 v212, 16, v71
	v_and_b32_e32 v213, 0xffff0000, v71
	v_pk_fma_f32 v[210:211], v[10:11], v[206:207], v[210:211]
	v_pk_fma_f32 v[212:213], v[12:13], v[208:209], v[212:213]
	v_cvt_pk_bf16_f32 v70, v210, v211
	v_cvt_pk_bf16_f32 v71, v212, v213
	v_lshlrev_b32_e32 v206, 16, v104
	v_and_b32_e32 v207, 0xffff0000, v104
	v_lshlrev_b32_e32 v208, 16, v105
	v_and_b32_e32 v209, 0xffff0000, v105
	v_lshlrev_b32_e32 v210, 16, v72
	v_and_b32_e32 v211, 0xffff0000, v72
	v_lshlrev_b32_e32 v212, 16, v73
	v_and_b32_e32 v213, 0xffff0000, v73
	v_pk_fma_f32 v[210:211], v[14:15], v[206:207], v[210:211]
	v_pk_fma_f32 v[212:213], v[16:17], v[208:209], v[212:213]
	v_cvt_pk_bf16_f32 v72, v210, v211
	v_cvt_pk_bf16_f32 v73, v212, v213
	v_lshlrev_b32_e32 v206, 16, v106
	v_and_b32_e32 v207, 0xffff0000, v106
	v_lshlrev_b32_e32 v208, 16, v107
	v_and_b32_e32 v209, 0xffff0000, v107
	v_lshlrev_b32_e32 v210, 16, v74
	v_and_b32_e32 v211, 0xffff0000, v74
	v_lshlrev_b32_e32 v212, 16, v75
	v_and_b32_e32 v213, 0xffff0000, v75
	v_pk_fma_f32 v[210:211], v[18:19], v[206:207], v[210:211]
	v_pk_fma_f32 v[212:213], v[20:21], v[208:209], v[212:213]
	v_cvt_pk_bf16_f32 v74, v210, v211
	v_cvt_pk_bf16_f32 v75, v212, v213
	v_lshlrev_b32_e32 v206, 16, v108
	v_and_b32_e32 v207, 0xffff0000, v108
	v_lshlrev_b32_e32 v208, 16, v109
	v_and_b32_e32 v209, 0xffff0000, v109
	v_lshlrev_b32_e32 v210, 16, v76
	v_and_b32_e32 v211, 0xffff0000, v76
	v_lshlrev_b32_e32 v212, 16, v77
	v_and_b32_e32 v213, 0xffff0000, v77
	v_pk_fma_f32 v[210:211], v[22:23], v[206:207], v[210:211]
; __device__ __forceinline__ unsigned cvtpk(float lo, float hi) { f32x2 v = {lo, hi}; bf16x2_t b = __builtin_convertvector(v, bf16x2_t); return __builtin_bit_cast(unsigned, b); }
; __device__ __forceinline__ void branch_phase(LAS unsigned char* lds, const bf16_t* __restrict__ O, const bf16_t* __restrict__ Wb, const bf16_t* __restrict__ Gt, bf16_t* __restrict__ MG, int tg, int wv) {
;     ...
;                 for (int n = 0; n < 4; ++n) { const u32x2 g = gv[m][n], sp = sum[m][n];
;                     const float s0_ = __builtin_bit_cast(float, sp.x << 16) + acc[m][n][0] * __builtin_bit_cast(float, g.x << 16), s1_ = __builtin_bit_cast(float, sp.x & 0xffff0000u) + acc[m][n][1] * __builtin_bit_cast(float, g.x & 0xffff0000u);
;                     const float s2_ = __builtin_bit_cast(float, sp.y << 16) + acc[m][n][2] * __builtin_bit_cast(float, g.y << 16), s3_ = __builtin_bit_cast(float, sp.y & 0xffff0000u) + acc[m][n][3] * __builtin_bit_cast(float, g.y & 0xffff0000u);
;                     sum[m][n] = (u32x2){cvtpk(s0_, s1_), cvtpk(s2_, s3_)}; }
	v_pk_fma_f32 v[212:213], v[24:25], v[208:209], v[212:213]
	v_cvt_pk_bf16_f32 v76, v210, v211
	v_cvt_pk_bf16_f32 v77, v212, v213
	v_lshlrev_b32_e32 v206, 16, v110
	v_and_b32_e32 v207, 0xffff0000, v110
	v_lshlrev_b32_e32 v208, 16, v111
	v_and_b32_e32 v209, 0xffff0000, v111
	v_lshlrev_b32_e32 v210, 16, v78
	v_and_b32_e32 v211, 0xffff0000, v78
	v_lshlrev_b32_e32 v212, 16, v79
	v_and_b32_e32 v213, 0xffff0000, v79
	v_pk_fma_f32 v[210:211], v[26:27], v[206:207], v[210:211]
	v_pk_fma_f32 v[212:213], v[28:29], v[208:209], v[212:213]
	v_cvt_pk_bf16_f32 v78, v210, v211
	v_cvt_pk_bf16_f32 v79, v212, v213
	v_lshlrev_b32_e32 v206, 16, v112
	v_and_b32_e32 v207, 0xffff0000, v112
	v_lshlrev_b32_e32 v208, 16, v113
	v_and_b32_e32 v209, 0xffff0000, v113
	v_lshlrev_b32_e32 v210, 16, v80
	v_and_b32_e32 v211, 0xffff0000, v80
	v_lshlrev_b32_e32 v212, 16, v81
	v_and_b32_e32 v213, 0xffff0000, v81
	v_pk_fma_f32 v[210:211], v[30:31], v[206:207], v[210:211]
	v_pk_fma_f32 v[212:213], v[32:33], v[208:209], v[212:213]
	v_cvt_pk_bf16_f32 v80, v210, v211
	v_cvt_pk_bf16_f32 v81, v212, v213
	v_lshlrev_b32_e32 v206, 16, v114
	v_and_b32_e32 v207, 0xffff0000, v114
	v_lshlrev_b32_e32 v208, 16, v115
	v_and_b32_e32 v209, 0xffff0000, v115
	v_lshlrev_b32_e32 v210, 16, v82
	v_and_b32_e32 v211, 0xffff0000, v82
	v_lshlrev_b32_e32 v212, 16, v83
	v_and_b32_e32 v213, 0xffff0000, v83
	v_pk_fma_f32 v[210:211], v[34:35], v[206:207], v[210:211]
	v_pk_fma_f32 v[212:213], v[36:37], v[208:209], v[212:213]
	v_cvt_pk_bf16_f32 v82, v210, v211
	v_cvt_pk_bf16_f32 v83, v212, v213
	v_lshlrev_b32_e32 v206, 16, v116
	v_and_b32_e32 v207, 0xffff0000, v116
	v_lshlrev_b32_e32 v208, 16, v117
	v_and_b32_e32 v209, 0xffff0000, v117
	v_lshlrev_b32_e32 v210, 16, v84
	v_and_b32_e32 v211, 0xffff0000, v84
	v_lshlrev_b32_e32 v212, 16, v85
	v_and_b32_e32 v213, 0xffff0000, v85
	v_pk_fma_f32 v[210:211], v[38:39], v[206:207], v[210:211]
	v_pk_fma_f32 v[212:213], v[40:41], v[208:209], v[212:213]
	v_cvt_pk_bf16_f32 v84, v210, v211
	v_cvt_pk_bf16_f32 v85, v212, v213
	v_lshlrev_b32_e32 v206, 16, v118
	v_and_b32_e32 v207, 0xffff0000, v118
	v_lshlrev_b32_e32 v208, 16, v119
	v_and_b32_e32 v209, 0xffff0000, v119
	v_lshlrev_b32_e32 v210, 16, v86
	v_and_b32_e32 v211, 0xffff0000, v86
	v_lshlrev_b32_e32 v212, 16, v87
	v_and_b32_e32 v213, 0xffff0000, v87
	v_pk_fma_f32 v[210:211], v[42:43], v[206:207], v[210:211]
	v_pk_fma_f32 v[212:213], v[44:45], v[208:209], v[212:213]
	v_cvt_pk_bf16_f32 v86, v210, v211
	v_cvt_pk_bf16_f32 v87, v212, v213
	v_lshlrev_b32_e32 v206, 16, v120
	v_and_b32_e32 v207, 0xffff0000, v120
	v_lshlrev_b32_e32 v208, 16, v121
	v_and_b32_e32 v209, 0xffff0000, v121
	v_lshlrev_b32_e32 v210, 16, v88
	v_and_b32_e32 v211, 0xffff0000, v88
	v_lshlrev_b32_e32 v212, 16, v89
	v_and_b32_e32 v213, 0xffff0000, v89
	v_pk_fma_f32 v[210:211], v[46:47], v[206:207], v[210:211]
	v_pk_fma_f32 v[212:213], v[48:49], v[208:209], v[212:213]
	v_cvt_pk_bf16_f32 v88, v210, v211
	v_cvt_pk_bf16_f32 v89, v212, v213
	v_lshlrev_b32_e32 v206, 16, v122
	v_and_b32_e32 v207, 0xffff0000, v122
	v_lshlrev_b32_e32 v208, 16, v123
	v_and_b32_e32 v209, 0xffff0000, v123
	v_lshlrev_b32_e32 v210, 16, v90
	v_and_b32_e32 v211, 0xffff0000, v90
	v_lshlrev_b32_e32 v212, 16, v91
	v_and_b32_e32 v213, 0xffff0000, v91
	v_pk_fma_f32 v[210:211], v[50:51], v[206:207], v[210:211]
	v_pk_fma_f32 v[212:213], v[52:53], v[208:209], v[212:213]
	v_cvt_pk_bf16_f32 v90, v210, v211
	v_cvt_pk_bf16_f32 v91, v212, v213
	v_lshlrev_b32_e32 v206, 16, v124
	v_and_b32_e32 v207, 0xffff0000, v124
	v_lshlrev_b32_e32 v208, 16, v125
	v_and_b32_e32 v209, 0xffff0000, v125
	v_lshlrev_b32_e32 v210, 16, v92
	v_and_b32_e32 v211, 0xffff0000, v92
	v_lshlrev_b32_e32 v212, 16, v93
	v_and_b32_e32 v213, 0xffff0000, v93
	v_pk_fma_f32 v[210:211], v[54:55], v[206:207], v[210:211]
	v_pk_fma_f32 v[212:213], v[56:57], v[208:209], v[212:213]
	v_cvt_pk_bf16_f32 v92, v210, v211
	v_cvt_pk_bf16_f32 v93, v212, v213
; __device__ __forceinline__ unsigned cvtpk(float lo, float hi) { f32x2 v = {lo, hi}; bf16x2_t b = __builtin_convertvector(v, bf16x2_t); return __builtin_bit_cast(unsigned, b); }
; __device__ __forceinline__ void branch_phase(LAS unsigned char* lds, const bf16_t* __restrict__ O, const bf16_t* __restrict__ Wb, const bf16_t* __restrict__ Gt, bf16_t* __restrict__ MG, int tg, int wv) {
;     ...
;     for (int tile = vb; tile < ntile; tile += G_) {
;     ...
;                 for (int n = 0; n < 4; ++n) { const u32x2 g = gv[m][n], sp = sum[m][n];
;                     const float s0_ = __builtin_bit_cast(float, sp.x << 16) + acc[m][n][0] * __builtin_bit_cast(float, g.x << 16), s1_ = __builtin_bit_cast(float, sp.x & 0xffff0000u) + acc[m][n][1] * __builtin_bit_cast(float, g.x & 0xffff0000u);
;                     const float s2_ = __builtin_bit_cast(float, sp.y << 16) + acc[m][n][2] * __builtin_bit_cast(float, g.y << 16), s3_ = __builtin_bit_cast(float, sp.y & 0xffff0000u) + acc[m][n][3] * __builtin_bit_cast(float, g.y & 0xffff0000u);
;                     sum[m][n] = (u32x2){cvtpk(s0_, s1_), cvtpk(s2_, s3_)}; }
;         }
;     ...
; #pragma unroll
;         for (int m = 0; m < 4; ++m)
; #pragma unroll
;             for (int np = 0; np < 2; ++np) { u32x2 a = sum[m][2 * np], b = sum[m][2 * np + 1];
;                 asm volatile("s_nop 1\n\tv_permlane16_swap_b32 %0, %1\n\ts_nop 1" : "+v"(a.x), "+v"(b.x));
;                 asm volatile("s_nop 1\n\tv_permlane16_swap_b32 %0, %1\n\ts_nop 1" : "+v"(a.y), "+v"(b.y));
;                 *(u32x4*)(MG + (size_t)(rt * 128 + wm * 64 + m * 16 + fr) * 1024 + ct * 256 + wn * 64 + np * 32 + (fq & 1) * 16 + (fq >> 1) * 8) = (u32x4){a.x, a.y, b.x, b.y}; }
;     }
	v_lshlrev_b32_e32 v206, 16, v126
	v_and_b32_e32 v207, 0xffff0000, v126
	v_lshlrev_b32_e32 v208, 16, v127
	v_and_b32_e32 v209, 0xffff0000, v127
	v_lshlrev_b32_e32 v210, 16, v94
	v_and_b32_e32 v211, 0xffff0000, v94
	v_lshlrev_b32_e32 v212, 16, v95
	v_and_b32_e32 v213, 0xffff0000, v95
	v_pk_fma_f32 v[210:211], v[58:59], v[206:207], v[210:211]
	v_pk_fma_f32 v[212:213], v[60:61], v[208:209], v[212:213]
	v_cvt_pk_bf16_f32 v94, v210, v211
	v_cvt_pk_bf16_f32 v95, v212, v213
	v_lshlrev_b32_e32 v206, 16, v128
	v_and_b32_e32 v207, 0xffff0000, v128
	v_lshlrev_b32_e32 v208, 16, v129
	v_and_b32_e32 v209, 0xffff0000, v129
	v_lshlrev_b32_e32 v210, 16, v96
	v_and_b32_e32 v211, 0xffff0000, v96
	v_lshlrev_b32_e32 v212, 16, v97
	v_and_b32_e32 v213, 0xffff0000, v97
	v_pk_fma_f32 v[210:211], v[62:63], v[206:207], v[210:211]
	v_pk_fma_f32 v[212:213], v[64:65], v[208:209], v[212:213]
	v_cvt_pk_bf16_f32 v96, v210, v211
	v_cvt_pk_bf16_f32 v97, v212, v213
	s_mov_b64 s[80:81], s[76:77]
	v_mov_b32_e32 v206, v66
	v_mov_b32_e32 v207, v67
	v_mov_b32_e32 v208, v68
	v_mov_b32_e32 v209, v69
	s_nop 1
	v_permlane16_swap_b32 v206, v208
	s_nop 1
	s_nop 1
	v_permlane16_swap_b32 v207, v209
	s_nop 1
	global_store_dwordx4 v205, v[206:209], s[80:81] offset:0
	s_nop 1
	v_mov_b32_e32 v206, v70
	v_mov_b32_e32 v207, v71
	v_mov_b32_e32 v208, v72
	v_mov_b32_e32 v209, v73
	s_nop 1
	v_permlane16_swap_b32 v206, v208
	s_nop 1
	s_nop 1
	v_permlane16_swap_b32 v207, v209
	s_nop 1
	global_store_dwordx4 v205, v[206:209], s[80:81] offset:64
	s_nop 1
	s_add_u32 s80, s80, 0x8000
	s_addc_u32 s81, s81, 0
	v_mov_b32_e32 v206, v74
	v_mov_b32_e32 v207, v75
	v_mov_b32_e32 v208, v76
	v_mov_b32_e32 v209, v77
	s_nop 1
	v_permlane16_swap_b32 v206, v208
	s_nop 1
	s_nop 1
	v_permlane16_swap_b32 v207, v209
	s_nop 1
	global_store_dwordx4 v205, v[206:209], s[80:81] offset:0
	s_nop 1
	v_mov_b32_e32 v206, v78
	v_mov_b32_e32 v207, v79
	v_mov_b32_e32 v208, v80
	v_mov_b32_e32 v209, v81
	s_nop 1
	v_permlane16_swap_b32 v206, v208
	s_nop 1
	s_nop 1
	v_permlane16_swap_b32 v207, v209
	s_nop 1
	global_store_dwordx4 v205, v[206:209], s[80:81] offset:64
	s_nop 1
	s_add_u32 s80, s80, 0x8000
	s_addc_u32 s81, s81, 0
	v_mov_b32_e32 v206, v82
	v_mov_b32_e32 v207, v83
	v_mov_b32_e32 v208, v84
	v_mov_b32_e32 v209, v85
	s_nop 1
	v_permlane16_swap_b32 v206, v208
	s_nop 1
	s_nop 1
	v_permlane16_swap_b32 v207, v209
	s_nop 1
	global_store_dwordx4 v205, v[206:209], s[80:81] offset:0
	s_nop 1
	v_mov_b32_e32 v206, v86
	v_mov_b32_e32 v207, v87
	v_mov_b32_e32 v208, v88
	v_mov_b32_e32 v209, v89
	s_nop 1
	v_permlane16_swap_b32 v206, v208
	s_nop 1
	s_nop 1
	v_permlane16_swap_b32 v207, v209
	s_nop 1
	global_store_dwordx4 v205, v[206:209], s[80:81] offset:64
	s_nop 1
	s_add_u32 s80, s80, 0x8000
	s_addc_u32 s81, s81, 0
	v_mov_b32_e32 v206, v90
	v_mov_b32_e32 v207, v91
	v_mov_b32_e32 v208, v92
	v_mov_b32_e32 v209, v93
	s_nop 1
	v_permlane16_swap_b32 v206, v208
	s_nop 1
	s_nop 1
	v_permlane16_swap_b32 v207, v209
	s_nop 1
	global_store_dwordx4 v205, v[206:209], s[80:81] offset:0
	s_nop 1
	v_mov_b32_e32 v206, v94
	v_mov_b32_e32 v207, v95
	v_mov_b32_e32 v208, v96
	v_mov_b32_e32 v209, v97
	s_nop 1
	v_permlane16_swap_b32 v206, v208
	s_nop 1
	s_nop 1
	v_permlane16_swap_b32 v207, v209
	s_nop 1
	global_store_dwordx4 v205, v[206:209], s[80:81] offset:64
	s_nop 1
	s_add_i32 s5, s5, s4
	s_cmp_lt_i32 s5, s6
	s_cbranch_scc0 .LBB0_283
	s_lshl_b32 s79, s62, 2
	s_add_u32 s74, s74, s79
	s_addc_u32 s75, s75, 0
	s_add_u32 s76, s76, s62
	s_addc_u32 s77, s77, 0
	s_mov_b32 s79, s82
	s_mov_b32 s82, s83
	s_mov_b32 s83, s84
	s_mov_b32 s84, s79
	s_mov_b32 s79, s85
	s_mov_b32 s85, s60
	s_mov_b32 s60, s61
	s_mov_b32 s61, s79
	v_mov_b32_e32 v206, v214
	v_mov_b32_e32 v214, v215
	v_mov_b32_e32 v215, v216
	v_mov_b32_e32 v216, v206
	v_mov_b32_e32 v206, v217
	v_mov_b32_e32 v217, v218
	v_mov_b32_e32 v218, v219
	v_mov_b32_e32 v219, v206
	s_branch .Lph6_tile
